# A/B test: GEMM priority flips inverted (load segment at prio 1, MFMA block at prio 0)
# speedup vs baseline: 1.0054x; 1.0054x over previous
; #define PG8_STAGE(bufoff, gbase, voff) do { _Pragma("unroll") for (int _i = 0; _i < 2; ++_i) \
;         __builtin_amdgcn_global_load_lds((const unsigned*)((const char*)(gbase) + (voff)[_i]), (LAS unsigned*)(lds + (bufoff) + ldsw + _i * 8192), 16, 0, 0); } while (0)
; #define PG8_LDA(dst, b, h) do { _Pragma("unroll") for (int m = 0; m < 4; ++m) _Pragma("unroll") for (int k = 0; k < 2; ++k) dst[m][k] = *(const LAS bf16x8*)(lds + PG8_SA(b, h) + aoff + m * 2048 + k * 1024); } while (0)
; #define PG8_LDB(dst, b, h) do { _Pragma("unroll") for (int n = 0; n < 2; ++n) _Pragma("unroll") for (int k = 0; k < 2; ++k) dst[n][k] = *(const LAS bf16x8*)(lds + PG8_SB(b, h) + boff + n * 2048 + k * 1024); } while (0)
; #define PG8_MMA(ai, bj, At, Bt) do { __builtin_amdgcn_s_setprio(1); _Pragma("unroll") for (int m = 0; m < 4; ++m) _Pragma("unroll") for (int n = 0; n < 2; ++n) _Pragma("unroll") for (int k = 0; k < 2; ++k) \
;         acc[ai][bj][m][n] = __builtin_amdgcn_mfma_f32_16x16x32_bf16(Bt[n][k], At[m][k], acc[ai][bj][m][n], 0, 0, 0); __builtin_amdgcn_s_setprio(0); } while (0)
; #define PG8_BAR __builtin_amdgcn_s_barrier()
; template <class Epi, bool ALIGN_EPI = true, bool SP2 = true>
; DI void gemm_phase(LAS unsigned char* lds, const Gemm g, const StaticOrder& S, const Epi& E) {
;     ...
;             const bool last = (t == nt - 2);
;             const char* a1 = cA + (size_t)(t + 1) * kstep;
;             const char* a2 = last ? nA : cA + (size_t)(t + 2) * kstep; const char* b2 = last ? nB : cB + (size_t)(t + 2) * kstep;
;             const char* a3 = a2 + kstep; const char* b3 = b2 + kstep;
;             if (Epi::MID) { if (t == (nt >> 1)) {
;                 if constexpr (ALIGN_EPI) { if (wr == 0) PG8_BAR; }
;                 E.mid(acc, cur, wr, wc, fr, fq);
;                 if constexpr (ALIGN_EPI) { if (wr == 1) PG8_BAR; } } }
;             if constexpr (SP2) {
;             PG8_LDB(B0, 0, 0); PG8_LDB(B1, 0, 1); PG8_SCHED; PG8_LDA(At, 0, 0); PG8_STAGE(PG8_SA(1, 1), a1 + hstepA, voffA);
;             PG8_WAIT_V(8); PG8_WAIT_L(0); PG8_BAR; PG8_MMA(0, 0, At, B0); PG8_MMA(0, 1, At, B1); PG8_BAR; PG8_SCHED;
;             PG8_LDA(At, 0, 1); PG8_STAGE(PG8_SB(0, 0), b2, voffB); PG8_STAGE(PG8_SB(0, 1), b2 + hstepB, voffB); PG8_STAGE(PG8_SA(0, 0), a2, voffA);
;             PG8_WAIT_V(8); PG8_WAIT_L(0); PG8_BAR; PG8_MMA(1, 0, At, B0); PG8_MMA(1, 1, At, B1); PG8_BAR; PG8_SCHED;
.LBB0_261:
	ds_read_b128 v[150:153], v147
	ds_read_b128 v[154:157], v147 offset:1024
	ds_read_b128 v[158:161], v147 offset:2048
	ds_read_b128 v[162:165], v147 offset:3072
	ds_read_b128 v[166:169], v148
	ds_read_b128 v[170:173], v148 offset:1024
	ds_read_b128 v[174:177], v148 offset:2048
	ds_read_b128 v[178:181], v148 offset:3072
	s_add_u32 s46, s34, 0xfff00080
	s_addc_u32 s47, s35, -1
	s_cmp_eq_u32 s78, 60
	s_cselect_b32 s49, s25, s47
	s_cselect_b32 s48, s74, s46
	s_cselect_b32 s47, s23, s77
	s_cselect_b32 s46, s75, s76
	v_lshl_add_u64 v[216:217], s[34:35], 0, v[136:137]
	s_add_i32 m0, s21, 0xc000
	ds_read_b128 v[182:185], v149
	ds_read_b128 v[186:189], v149 offset:1024
	ds_read_b128 v[192:195], v149 offset:2048
	ds_read_b128 v[196:199], v149 offset:3072
	ds_read_b128 v[200:203], v149 offset:4096
	ds_read_b128 v[204:207], v149 offset:5120
	ds_read_b128 v[208:211], v149 offset:6144
	ds_read_b128 v[212:215], v149 offset:7168
	global_load_lds_dwordx4 v[216:217], off
	v_lshl_add_u64 v[216:217], s[34:35], 0, v[138:139]
	s_add_i32 m0, s21, 0xe000
	s_nop 0
	global_load_lds_dwordx4 v[216:217], off
	s_waitcnt vmcnt(8)
	s_waitcnt lgkmcnt(0)
	s_barrier
	s_setprio 0
	s_waitcnt lgkmcnt(0)
	v_mfma_f32_16x16x32_bf16 v[124:127], v[150:153], v[182:185], v[124:127]
	v_mfma_f32_16x16x32_bf16 v[120:123], v[158:161], v[182:185], v[120:123]
	v_mfma_f32_16x16x32_bf16 v[116:119], v[150:153], v[192:195], v[116:119]
	v_mfma_f32_16x16x32_bf16 v[112:115], v[158:161], v[192:195], v[112:115]
	v_mfma_f32_16x16x32_bf16 v[100:103], v[150:153], v[200:203], v[100:103]
	v_mfma_f32_16x16x32_bf16 v[96:99], v[158:161], v[200:203], v[96:99]
	v_mfma_f32_16x16x32_bf16 v[84:87], v[150:153], v[208:211], v[84:87]
	v_mfma_f32_16x16x32_bf16 v[80:83], v[158:161], v[208:211], v[80:83]
	v_mfma_f32_16x16x32_bf16 v[124:127], v[154:157], v[186:189], v[124:127]
	v_mfma_f32_16x16x32_bf16 v[120:123], v[162:165], v[186:189], v[120:123]
	v_mfma_f32_16x16x32_bf16 v[116:119], v[154:157], v[196:199], v[116:119]
	v_mfma_f32_16x16x32_bf16 v[112:115], v[162:165], v[196:199], v[112:115]
	v_mfma_f32_16x16x32_bf16 v[100:103], v[154:157], v[204:207], v[100:103]
	v_mfma_f32_16x16x32_bf16 v[96:99], v[162:165], v[204:207], v[96:99]
	v_mfma_f32_16x16x32_bf16 v[84:87], v[154:157], v[212:215], v[84:87]
	v_mfma_f32_16x16x32_bf16 v[80:83], v[162:165], v[212:215], v[80:83]
	v_mfma_f32_16x16x32_bf16 v[108:111], v[166:169], v[182:185], v[108:111]
	v_mfma_f32_16x16x32_bf16 v[104:107], v[174:177], v[182:185], v[104:107]
	v_mfma_f32_16x16x32_bf16 v[92:95], v[166:169], v[192:195], v[92:95]
	v_mfma_f32_16x16x32_bf16 v[88:91], v[174:177], v[192:195], v[88:91]
	v_mfma_f32_16x16x32_bf16 v[76:79], v[166:169], v[200:203], v[76:79]
	v_mfma_f32_16x16x32_bf16 v[72:75], v[174:177], v[200:203], v[72:75]
	v_mfma_f32_16x16x32_bf16 v[68:71], v[166:169], v[208:211], v[68:71]
	v_mfma_f32_16x16x32_bf16 v[64:67], v[174:177], v[208:211], v[64:67]
	v_mfma_f32_16x16x32_bf16 v[108:111], v[170:173], v[186:189], v[108:111]
	v_mfma_f32_16x16x32_bf16 v[104:107], v[178:181], v[186:189], v[104:107]
	v_mfma_f32_16x16x32_bf16 v[92:95], v[170:173], v[196:199], v[92:95]
	v_mfma_f32_16x16x32_bf16 v[88:91], v[178:181], v[196:199], v[88:91]
	v_mfma_f32_16x16x32_bf16 v[76:79], v[170:173], v[204:207], v[76:79]
	v_mfma_f32_16x16x32_bf16 v[72:75], v[178:181], v[204:207], v[72:75]
	v_mfma_f32_16x16x32_bf16 v[68:71], v[170:173], v[212:215], v[68:71]
	v_mfma_f32_16x16x32_bf16 v[64:67], v[178:181], v[212:215], v[64:67]
	s_setprio 1
	s_barrier
	s_add_i32 s79, s70, s51
	v_lshl_add_u64 v[216:217], s[46:47], 0, v[132:133]
	s_mov_b32 m0, s79
	ds_read_b128 v[182:185], v149 offset:16384
	ds_read_b128 v[186:189], v149 offset:17408
	ds_read_b128 v[192:195], v149 offset:18432
	ds_read_b128 v[196:199], v149 offset:19456
	ds_read_b128 v[200:203], v149 offset:20480
	ds_read_b128 v[204:207], v149 offset:21504
	ds_read_b128 v[208:211], v149 offset:22528
	ds_read_b128 v[212:215], v149 offset:23552
	global_load_lds_dwordx4 v[216:217], off
	s_add_i32 m0, s79, 0x2000
	s_add_u32 s80, s46, 0x100000
	v_lshl_add_u64 v[218:219], s[46:47], 0, v[128:129]
	s_addc_u32 s81, s47, 0
	s_add_i32 s79, s71, s51
	global_load_lds_dwordx4 v[218:219], off
	v_lshl_add_u64 v[220:221], s[80:81], 0, v[132:133]
	s_mov_b32 m0, s79
	v_lshl_add_u64 v[222:223], s[48:49], 0, v[130:131]
	global_load_lds_dwordx4 v[220:221], off
	v_lshl_add_u64 v[220:221], s[80:81], 0, v[128:129]
	s_add_i32 m0, s79, 0x2000
	s_nop 0
	global_load_lds_dwordx4 v[220:221], off
	v_lshl_add_u64 v[220:221], s[48:49], 0, v[134:135]
	s_mov_b32 m0, s21
	s_nop 0
	global_load_lds_dwordx4 v[220:221], off
	s_mov_b32 m0, s62
	s_nop 0
	global_load_lds_dwordx4 v[222:223], off
	s_waitcnt vmcnt(8)
	s_waitcnt lgkmcnt(0)
	s_barrier
; #define PG8_STAGE(bufoff, gbase, voff) do { _Pragma("unroll") for (int _i = 0; _i < 2; ++_i) \
;         __builtin_amdgcn_global_load_lds((const unsigned*)((const char*)(gbase) + (voff)[_i]), (LAS unsigned*)(lds + (bufoff) + ldsw + _i * 8192), 16, 0, 0); } while (0)
; #define PG8_LDA(dst, b, h) do { _Pragma("unroll") for (int m = 0; m < 4; ++m) _Pragma("unroll") for (int k = 0; k < 2; ++k) dst[m][k] = *(const LAS bf16x8*)(lds + PG8_SA(b, h) + aoff + m * 2048 + k * 1024); } while (0)
; #define PG8_LDB(dst, b, h) do { _Pragma("unroll") for (int n = 0; n < 2; ++n) _Pragma("unroll") for (int k = 0; k < 2; ++k) dst[n][k] = *(const LAS bf16x8*)(lds + PG8_SB(b, h) + boff + n * 2048 + k * 1024); } while (0)
; #define PG8_MMA(ai, bj, At, Bt) do { __builtin_amdgcn_s_setprio(1); _Pragma("unroll") for (int m = 0; m < 4; ++m) _Pragma("unroll") for (int n = 0; n < 2; ++n) _Pragma("unroll") for (int k = 0; k < 2; ++k) \
;         acc[ai][bj][m][n] = __builtin_amdgcn_mfma_f32_16x16x32_bf16(Bt[n][k], At[m][k], acc[ai][bj][m][n], 0, 0, 0); __builtin_amdgcn_s_setprio(0); } while (0)
; #define PG8_WAIT_V(n) asm volatile("s_waitcnt vmcnt(" #n ")" ::: "memory")
; #define PG8_WAIT_L(n) asm volatile("s_waitcnt lgkmcnt(" #n ")" ::: "memory")
; #define PG8_BAR __builtin_amdgcn_s_barrier()
; #define PG8_SCHED __builtin_amdgcn_sched_barrier(0)
; template <class Epi, bool ALIGN_EPI = true, bool SP2 = true>
; DI void gemm_phase(LAS unsigned char* lds, const Gemm g, const StaticOrder& S, const Epi& E) {
;     ...
;             PG8_WAIT_V(8); PG8_WAIT_L(0); PG8_BAR; PG8_MMA(1, 0, At, B0); PG8_MMA(1, 1, At, B1); PG8_BAR; PG8_SCHED;
;             PG8_LDB(B0, 1, 0); PG8_LDB(B1, 1, 1); PG8_SCHED; PG8_LDA(At, 1, 0); PG8_STAGE(PG8_SA(0, 1), a2 + hstepA, voffA);
;             PG8_WAIT_V(8); PG8_WAIT_L(0); PG8_BAR; PG8_MMA(0, 0, At, B0); PG8_MMA(0, 1, At, B1); PG8_BAR; PG8_SCHED;
	s_setprio 0
	s_waitcnt lgkmcnt(0)
	v_mfma_f32_16x16x32_bf16 v[60:63], v[150:153], v[182:185], v[60:63]
	v_mfma_f32_16x16x32_bf16 v[56:59], v[158:161], v[182:185], v[56:59]
	v_mfma_f32_16x16x32_bf16 v[52:55], v[150:153], v[192:195], v[52:55]
	v_mfma_f32_16x16x32_bf16 v[48:51], v[158:161], v[192:195], v[48:51]
	v_mfma_f32_16x16x32_bf16 v[36:39], v[150:153], v[200:203], v[36:39]
	v_mfma_f32_16x16x32_bf16 v[32:35], v[158:161], v[200:203], v[32:35]
	v_mfma_f32_16x16x32_bf16 v[20:23], v[150:153], v[208:211], v[20:23]
	v_mfma_f32_16x16x32_bf16 v[16:19], v[158:161], v[208:211], v[16:19]
	v_mfma_f32_16x16x32_bf16 v[60:63], v[154:157], v[186:189], v[60:63]
	v_mfma_f32_16x16x32_bf16 v[56:59], v[162:165], v[186:189], v[56:59]
	v_mfma_f32_16x16x32_bf16 v[52:55], v[154:157], v[196:199], v[52:55]
	v_mfma_f32_16x16x32_bf16 v[48:51], v[162:165], v[196:199], v[48:51]
	v_mfma_f32_16x16x32_bf16 v[36:39], v[154:157], v[204:207], v[36:39]
	v_mfma_f32_16x16x32_bf16 v[32:35], v[162:165], v[204:207], v[32:35]
	v_mfma_f32_16x16x32_bf16 v[20:23], v[154:157], v[212:215], v[20:23]
	v_mfma_f32_16x16x32_bf16 v[16:19], v[162:165], v[212:215], v[16:19]
	v_mfma_f32_16x16x32_bf16 v[44:47], v[166:169], v[182:185], v[44:47]
	v_mfma_f32_16x16x32_bf16 v[40:43], v[174:177], v[182:185], v[40:43]
	v_mfma_f32_16x16x32_bf16 v[28:31], v[166:169], v[192:195], v[28:31]
	v_mfma_f32_16x16x32_bf16 v[24:27], v[174:177], v[192:195], v[24:27]
	v_mfma_f32_16x16x32_bf16 v[12:15], v[166:169], v[200:203], v[12:15]
	v_mfma_f32_16x16x32_bf16 v[8:11], v[174:177], v[200:203], v[8:11]
	v_mfma_f32_16x16x32_bf16 v[4:7], v[166:169], v[208:211], v[4:7]
	v_mfma_f32_16x16x32_bf16 v[0:3], v[174:177], v[208:211], v[0:3]
	v_mfma_f32_16x16x32_bf16 v[44:47], v[170:173], v[186:189], v[44:47]
	v_mfma_f32_16x16x32_bf16 v[40:43], v[178:181], v[186:189], v[40:43]
	v_mfma_f32_16x16x32_bf16 v[28:31], v[170:173], v[196:199], v[28:31]
	v_mfma_f32_16x16x32_bf16 v[24:27], v[178:181], v[196:199], v[24:27]
	v_mfma_f32_16x16x32_bf16 v[12:15], v[170:173], v[204:207], v[12:15]
	v_mfma_f32_16x16x32_bf16 v[8:11], v[178:181], v[204:207], v[8:11]
	v_mfma_f32_16x16x32_bf16 v[4:7], v[170:173], v[212:215], v[4:7]
	v_mfma_f32_16x16x32_bf16 v[0:3], v[178:181], v[212:215], v[0:3]
	s_setprio 1
	s_barrier
	s_add_i32 s79, 0, 0x18000
	s_add_i32 s80, 0, 0x1c000
	v_add_u32_e32 v162, s79, v145
	v_add_u32_e32 v178, s80, v145
	ds_read_b128 v[150:153], v162
	ds_read_b128 v[154:157], v162 offset:1024
	ds_read_b128 v[158:161], v162 offset:2048
	ds_read_b128 v[162:165], v162 offset:3072
	ds_read_b128 v[166:169], v178
	ds_read_b128 v[170:173], v178 offset:1024
	ds_read_b128 v[174:177], v178 offset:2048
	ds_read_b128 v[178:181], v178 offset:3072
	s_add_u32 s48, s48, 0x100000
	s_addc_u32 s49, s49, 0
	s_mov_b32 m0, s63
	v_lshl_add_u64 v[226:227], s[48:49], 0, v[134:135]
	ds_read_b128 v[182:185], v149 offset:32768
	ds_read_b128 v[186:189], v149 offset:33792
	ds_read_b128 v[192:195], v149 offset:34816
	ds_read_b128 v[196:199], v149 offset:35840
	ds_read_b128 v[200:203], v149 offset:36864
	ds_read_b128 v[204:207], v149 offset:37888
	ds_read_b128 v[208:211], v149 offset:38912
	ds_read_b128 v[212:215], v149 offset:39936
	global_load_lds_dwordx4 v[226:227], off
	v_lshl_add_u64 v[226:227], s[48:49], 0, v[130:131]
	s_mov_b32 m0, s64
	s_nop 0
	global_load_lds_dwordx4 v[226:227], off
	s_waitcnt vmcnt(8)
	s_waitcnt lgkmcnt(0)
	s_barrier
	s_setprio 0
	s_waitcnt lgkmcnt(0)
	v_mfma_f32_16x16x32_bf16 v[124:127], v[150:153], v[182:185], v[124:127]
	v_mfma_f32_16x16x32_bf16 v[120:123], v[158:161], v[182:185], v[120:123]
	v_mfma_f32_16x16x32_bf16 v[116:119], v[150:153], v[192:195], v[116:119]
	v_mfma_f32_16x16x32_bf16 v[112:115], v[158:161], v[192:195], v[112:115]
	v_mfma_f32_16x16x32_bf16 v[100:103], v[150:153], v[200:203], v[100:103]
	v_mfma_f32_16x16x32_bf16 v[96:99], v[158:161], v[200:203], v[96:99]
	v_mfma_f32_16x16x32_bf16 v[84:87], v[150:153], v[208:211], v[84:87]
	v_mfma_f32_16x16x32_bf16 v[80:83], v[158:161], v[208:211], v[80:83]
	v_mfma_f32_16x16x32_bf16 v[124:127], v[154:157], v[186:189], v[124:127]
	v_mfma_f32_16x16x32_bf16 v[120:123], v[162:165], v[186:189], v[120:123]
	v_mfma_f32_16x16x32_bf16 v[116:119], v[154:157], v[196:199], v[116:119]
	v_mfma_f32_16x16x32_bf16 v[112:115], v[162:165], v[196:199], v[112:115]
	v_mfma_f32_16x16x32_bf16 v[100:103], v[154:157], v[204:207], v[100:103]
	v_mfma_f32_16x16x32_bf16 v[96:99], v[162:165], v[204:207], v[96:99]
	v_mfma_f32_16x16x32_bf16 v[84:87], v[154:157], v[212:215], v[84:87]
	v_mfma_f32_16x16x32_bf16 v[80:83], v[162:165], v[212:215], v[80:83]
	v_mfma_f32_16x16x32_bf16 v[108:111], v[166:169], v[182:185], v[108:111]
	v_mfma_f32_16x16x32_bf16 v[104:107], v[174:177], v[182:185], v[104:107]
	v_mfma_f32_16x16x32_bf16 v[92:95], v[166:169], v[192:195], v[92:95]
	v_mfma_f32_16x16x32_bf16 v[88:91], v[174:177], v[192:195], v[88:91]
	v_mfma_f32_16x16x32_bf16 v[76:79], v[166:169], v[200:203], v[76:79]
	v_mfma_f32_16x16x32_bf16 v[72:75], v[174:177], v[200:203], v[72:75]
	v_mfma_f32_16x16x32_bf16 v[68:71], v[166:169], v[208:211], v[68:71]
	v_mfma_f32_16x16x32_bf16 v[64:67], v[174:177], v[208:211], v[64:67]
	v_mfma_f32_16x16x32_bf16 v[108:111], v[170:173], v[186:189], v[108:111]
	v_mfma_f32_16x16x32_bf16 v[104:107], v[178:181], v[186:189], v[104:107]
	v_mfma_f32_16x16x32_bf16 v[92:95], v[170:173], v[196:199], v[92:95]
	v_mfma_f32_16x16x32_bf16 v[88:91], v[178:181], v[196:199], v[88:91]
	v_mfma_f32_16x16x32_bf16 v[76:79], v[170:173], v[204:207], v[76:79]
	v_mfma_f32_16x16x32_bf16 v[72:75], v[178:181], v[204:207], v[72:75]
	v_mfma_f32_16x16x32_bf16 v[68:71], v[170:173], v[212:215], v[68:71]
	v_mfma_f32_16x16x32_bf16 v[64:67], v[178:181], v[212:215], v[64:67]
	s_setprio 1
	s_barrier
; #define PG8_STAGE(bufoff, gbase, voff) do { _Pragma("unroll") for (int _i = 0; _i < 2; ++_i) \
;         __builtin_amdgcn_global_load_lds((const unsigned*)((const char*)(gbase) + (voff)[_i]), (LAS unsigned*)(lds + (bufoff) + ldsw + _i * 8192), 16, 0, 0); } while (0)
; #define PG8_LDA(dst, b, h) do { _Pragma("unroll") for (int m = 0; m < 4; ++m) _Pragma("unroll") for (int k = 0; k < 2; ++k) dst[m][k] = *(const LAS bf16x8*)(lds + PG8_SA(b, h) + aoff + m * 2048 + k * 1024); } while (0)
; #define PG8_MMA(ai, bj, At, Bt) do { __builtin_amdgcn_s_setprio(1); _Pragma("unroll") for (int m = 0; m < 4; ++m) _Pragma("unroll") for (int n = 0; n < 2; ++n) _Pragma("unroll") for (int k = 0; k < 2; ++k) \
;         acc[ai][bj][m][n] = __builtin_amdgcn_mfma_f32_16x16x32_bf16(Bt[n][k], At[m][k], acc[ai][bj][m][n], 0, 0, 0); __builtin_amdgcn_s_setprio(0); } while (0)
; #define PG8_WAIT_V(n) asm volatile("s_waitcnt vmcnt(" #n ")" ::: "memory")
; #define PG8_WAIT_L(n) asm volatile("s_waitcnt lgkmcnt(" #n ")" ::: "memory")
; #define PG8_BAR __builtin_amdgcn_s_barrier()
; #define PG8_SCHED __builtin_amdgcn_sched_barrier(0)
; template <class Epi, bool ALIGN_EPI = true, bool SP2 = true>
; DI void gemm_phase(LAS unsigned char* lds, const Gemm g, const StaticOrder& S, const Epi& E) {
;     ...
;             PG8_LDA(At, 1, 1); PG8_STAGE(PG8_SB(1, 0), b3, voffB); PG8_STAGE(PG8_SB(1, 1), b3 + hstepB, voffB); PG8_STAGE(PG8_SA(1, 0), a3, voffA);
;             PG8_WAIT_V(8); PG8_WAIT_L(0); PG8_BAR; PG8_MMA(1, 0, At, B0); PG8_MMA(1, 1, At, B1); PG8_BAR; PG8_SCHED;
;     ...
;         if constexpr (ALIGN_EPI) { if (wr == 0) PG8_BAR; }
	s_add_i32 s48, s79, s51
	v_lshl_add_u64 v[216:217], v[216:217], 0, s[10:11]
	s_mov_b32 m0, s48
	ds_read_b128 v[182:185], v149 offset:49152
	ds_read_b128 v[186:189], v149 offset:50176
	ds_read_b128 v[192:195], v149 offset:51200
	ds_read_b128 v[196:199], v149 offset:52224
	ds_read_b128 v[200:203], v149 offset:53248
	ds_read_b128 v[204:207], v149 offset:54272
	ds_read_b128 v[208:211], v149 offset:55296
	ds_read_b128 v[212:215], v149 offset:56320
	global_load_lds_dwordx4 v[216:217], off
	s_add_i32 m0, s48, 0x2000
	s_add_u32 s46, s46, 0x100080
	v_lshl_add_u64 v[216:217], v[218:219], 0, s[10:11]
	s_addc_u32 s47, s47, 0
	s_add_i32 s48, s80, s51
	global_load_lds_dwordx4 v[216:217], off
	v_lshl_add_u64 v[216:217], s[46:47], 0, v[132:133]
	s_mov_b32 m0, s48
	s_nop 0
	global_load_lds_dwordx4 v[216:217], off
	v_lshl_add_u64 v[216:217], s[46:47], 0, v[128:129]
	s_add_i32 m0, s48, 0x2000
	s_nop 0
	global_load_lds_dwordx4 v[216:217], off
	v_lshl_add_u64 v[216:217], v[220:221], 0, s[10:11]
	s_mov_b32 m0, s66
	s_nop 0
	global_load_lds_dwordx4 v[216:217], off
	v_lshl_add_u64 v[216:217], v[222:223], 0, s[10:11]
	s_mov_b32 m0, s67
	s_nop 0
	global_load_lds_dwordx4 v[216:217], off
	s_waitcnt vmcnt(8)
	s_waitcnt lgkmcnt(0)
	s_barrier
	s_setprio 0
	s_waitcnt lgkmcnt(0)
	v_mfma_f32_16x16x32_bf16 v[60:63], v[150:153], v[182:185], v[60:63]
	v_mfma_f32_16x16x32_bf16 v[56:59], v[158:161], v[182:185], v[56:59]
	v_mfma_f32_16x16x32_bf16 v[52:55], v[150:153], v[192:195], v[52:55]
	v_mfma_f32_16x16x32_bf16 v[48:51], v[158:161], v[192:195], v[48:51]
	v_mfma_f32_16x16x32_bf16 v[36:39], v[150:153], v[200:203], v[36:39]
	v_mfma_f32_16x16x32_bf16 v[32:35], v[158:161], v[200:203], v[32:35]
	v_mfma_f32_16x16x32_bf16 v[20:23], v[150:153], v[208:211], v[20:23]
	v_mfma_f32_16x16x32_bf16 v[16:19], v[158:161], v[208:211], v[16:19]
	v_mfma_f32_16x16x32_bf16 v[60:63], v[154:157], v[186:189], v[60:63]
	v_mfma_f32_16x16x32_bf16 v[56:59], v[162:165], v[186:189], v[56:59]
	v_mfma_f32_16x16x32_bf16 v[52:55], v[154:157], v[196:199], v[52:55]
	v_mfma_f32_16x16x32_bf16 v[48:51], v[162:165], v[196:199], v[48:51]
	v_mfma_f32_16x16x32_bf16 v[36:39], v[154:157], v[204:207], v[36:39]
	v_mfma_f32_16x16x32_bf16 v[32:35], v[162:165], v[204:207], v[32:35]
	v_mfma_f32_16x16x32_bf16 v[20:23], v[154:157], v[212:215], v[20:23]
	v_mfma_f32_16x16x32_bf16 v[16:19], v[162:165], v[212:215], v[16:19]
	v_mfma_f32_16x16x32_bf16 v[44:47], v[166:169], v[182:185], v[44:47]
	v_mfma_f32_16x16x32_bf16 v[40:43], v[174:177], v[182:185], v[40:43]
	v_mfma_f32_16x16x32_bf16 v[28:31], v[166:169], v[192:195], v[28:31]
	v_mfma_f32_16x16x32_bf16 v[24:27], v[174:177], v[192:195], v[24:27]
	v_mfma_f32_16x16x32_bf16 v[12:15], v[166:169], v[200:203], v[12:15]
	v_mfma_f32_16x16x32_bf16 v[8:11], v[174:177], v[200:203], v[8:11]
	v_mfma_f32_16x16x32_bf16 v[4:7], v[166:169], v[208:211], v[4:7]
	v_mfma_f32_16x16x32_bf16 v[0:3], v[174:177], v[208:211], v[0:3]
	v_mfma_f32_16x16x32_bf16 v[44:47], v[170:173], v[186:189], v[44:47]
	v_mfma_f32_16x16x32_bf16 v[40:43], v[178:181], v[186:189], v[40:43]
	v_mfma_f32_16x16x32_bf16 v[28:31], v[170:173], v[196:199], v[28:31]
	v_mfma_f32_16x16x32_bf16 v[24:27], v[178:181], v[196:199], v[24:27]
	v_mfma_f32_16x16x32_bf16 v[12:15], v[170:173], v[204:207], v[12:15]
	v_mfma_f32_16x16x32_bf16 v[8:11], v[178:181], v[204:207], v[8:11]
	v_mfma_f32_16x16x32_bf16 v[4:7], v[170:173], v[212:215], v[4:7]
	v_mfma_f32_16x16x32_bf16 v[0:3], v[178:181], v[212:215], v[0:3]
	s_setprio 1
	s_barrier
	s_add_i32 s78, s78, 2
	s_add_u32 s34, s34, 0x100
	s_addc_u32 s35, s35, 0
	s_add_u32 s76, s76, 0x100
	s_addc_u32 s77, s77, 0
	s_cmp_gt_u32 s78, 61
	s_cbranch_scc0 .LBB0_261
	s_and_b64 vcc, exec, s[18:19]
	s_cbranch_vccz .LBB0_264
	s_barrier

; #define PG8_STAGE(bufoff, gbase, voff) do { _Pragma("unroll") for (int _i = 0; _i < 2; ++_i) \
;         __builtin_amdgcn_global_load_lds((const unsigned*)((const char*)(gbase) + (voff)[_i]), (LAS unsigned*)(lds + (bufoff) + ldsw + _i * 8192), 16, 0, 0); } while (0)
; #define PG8_LDA(dst, b, h) do { _Pragma("unroll") for (int m = 0; m < 4; ++m) _Pragma("unroll") for (int k = 0; k < 2; ++k) dst[m][k] = *(const LAS bf16x8*)(lds + PG8_SA(b, h) + aoff + m * 2048 + k * 1024); } while (0)
; #define PG8_LDB(dst, b, h) do { _Pragma("unroll") for (int n = 0; n < 2; ++n) _Pragma("unroll") for (int k = 0; k < 2; ++k) dst[n][k] = *(const LAS bf16x8*)(lds + PG8_SB(b, h) + boff + n * 2048 + k * 1024); } while (0)
; #define PG8_MMA(ai, bj, At, Bt) do { __builtin_amdgcn_s_setprio(1); _Pragma("unroll") for (int m = 0; m < 4; ++m) _Pragma("unroll") for (int n = 0; n < 2; ++n) _Pragma("unroll") for (int k = 0; k < 2; ++k) \
;         acc[ai][bj][m][n] = __builtin_amdgcn_mfma_f32_16x16x32_bf16(Bt[n][k], At[m][k], acc[ai][bj][m][n], 0, 0, 0); __builtin_amdgcn_s_setprio(0); } while (0)
; #define PG8_BAR __builtin_amdgcn_s_barrier()
; template <class Epi, bool ALIGN_EPI = true, bool SP2 = true>
; DI void gemm_phase(LAS unsigned char* lds, const Gemm g, const StaticOrder& S, const Epi& E) {
;     ...
;             const bool last = (t == nt - 2);
;             const char* a1 = cA + (size_t)(t + 1) * kstep;
;             const char* a2 = last ? nA : cA + (size_t)(t + 2) * kstep; const char* b2 = last ? nB : cB + (size_t)(t + 2) * kstep;
;             const char* a3 = a2 + kstep; const char* b3 = b2 + kstep;
;             if (Epi::MID) { if (t == (nt >> 1)) {
;                 if constexpr (ALIGN_EPI) { if (wr == 0) PG8_BAR; }
;                 E.mid(acc, cur, wr, wc, fr, fq);
;                 if constexpr (ALIGN_EPI) { if (wr == 1) PG8_BAR; } } }
;             if constexpr (SP2) {
;             PG8_LDB(B0, 0, 0); PG8_LDB(B1, 0, 1); PG8_SCHED; PG8_LDA(At, 0, 0); PG8_STAGE(PG8_SA(1, 1), a1 + hstepA, voffA);
;             PG8_WAIT_V(8); PG8_WAIT_L(0); PG8_BAR; PG8_MMA(0, 0, At, B0); PG8_MMA(0, 1, At, B1); PG8_BAR; PG8_SCHED;
;             PG8_LDA(At, 0, 1); PG8_STAGE(PG8_SB(0, 0), b2, voffB); PG8_STAGE(PG8_SB(0, 1), b2 + hstepB, voffB); PG8_STAGE(PG8_SA(0, 0), a2, voffA);
;             PG8_WAIT_V(8); PG8_WAIT_L(0); PG8_BAR; PG8_MMA(1, 0, At, B0); PG8_MMA(1, 1, At, B1); PG8_BAR; PG8_SCHED;
.LBB0_334:
	ds_read_b128 v[162:165], v158
	ds_read_b128 v[166:169], v158 offset:1024
	ds_read_b128 v[170:173], v158 offset:2048
	ds_read_b128 v[174:177], v158 offset:3072
	ds_read_b128 v[178:181], v159
	ds_read_b128 v[182:185], v159 offset:1024
	ds_read_b128 v[186:189], v159 offset:2048
	ds_read_b128 v[192:195], v159 offset:3072
	s_add_u32 s30, s0, 0xffb80080
	s_addc_u32 s31, s1, -1
	s_cmp_eq_u32 s76, 12
	s_cselect_b32 s35, s25, s31
	s_cselect_b32 s34, s24, s30
	s_cselect_b32 s31, s23, s75
	s_cselect_b32 s30, s73, s74
	v_lshl_add_u64 v[230:231], s[0:1], 0, v[136:137]
	s_add_i32 m0, s49, 0xc000
	ds_read_b128 v[196:199], v160
	ds_read_b128 v[200:203], v160 offset:1024
	ds_read_b128 v[204:207], v160 offset:2048
	ds_read_b128 v[208:211], v160 offset:3072
	ds_read_b128 v[212:215], v160 offset:4096
	ds_read_b128 v[216:219], v160 offset:5120
	ds_read_b128 v[220:223], v160 offset:6144
	ds_read_b128 v[226:229], v160 offset:7168
	global_load_lds_dwordx4 v[230:231], off
	v_lshl_add_u64 v[230:231], s[0:1], 0, v[138:139]
	s_add_i32 m0, s49, 0xe000
	s_nop 0
	global_load_lds_dwordx4 v[230:231], off
	s_waitcnt vmcnt(8)
	s_waitcnt lgkmcnt(0)
	s_barrier
	s_setprio 0
	s_waitcnt lgkmcnt(0)
	v_mfma_f32_16x16x32_bf16 v[124:127], v[162:165], v[196:199], v[124:127]
	v_mfma_f32_16x16x32_bf16 v[120:123], v[170:173], v[196:199], v[120:123]
	v_mfma_f32_16x16x32_bf16 v[116:119], v[162:165], v[204:207], v[116:119]
	v_mfma_f32_16x16x32_bf16 v[112:115], v[170:173], v[204:207], v[112:115]
	v_mfma_f32_16x16x32_bf16 v[100:103], v[162:165], v[212:215], v[100:103]
	v_mfma_f32_16x16x32_bf16 v[96:99], v[170:173], v[212:215], v[96:99]
	v_mfma_f32_16x16x32_bf16 v[84:87], v[162:165], v[220:223], v[84:87]
	v_mfma_f32_16x16x32_bf16 v[80:83], v[170:173], v[220:223], v[80:83]
	v_mfma_f32_16x16x32_bf16 v[124:127], v[166:169], v[200:203], v[124:127]
	v_mfma_f32_16x16x32_bf16 v[120:123], v[174:177], v[200:203], v[120:123]
	v_mfma_f32_16x16x32_bf16 v[116:119], v[166:169], v[208:211], v[116:119]
	v_mfma_f32_16x16x32_bf16 v[112:115], v[174:177], v[208:211], v[112:115]
	v_mfma_f32_16x16x32_bf16 v[100:103], v[166:169], v[216:219], v[100:103]
	v_mfma_f32_16x16x32_bf16 v[96:99], v[174:177], v[216:219], v[96:99]
	v_mfma_f32_16x16x32_bf16 v[84:87], v[166:169], v[226:229], v[84:87]
	v_mfma_f32_16x16x32_bf16 v[80:83], v[174:177], v[226:229], v[80:83]
	v_mfma_f32_16x16x32_bf16 v[108:111], v[178:181], v[196:199], v[108:111]
	v_mfma_f32_16x16x32_bf16 v[104:107], v[186:189], v[196:199], v[104:107]
	v_mfma_f32_16x16x32_bf16 v[92:95], v[178:181], v[204:207], v[92:95]
	v_mfma_f32_16x16x32_bf16 v[88:91], v[186:189], v[204:207], v[88:91]
	v_mfma_f32_16x16x32_bf16 v[76:79], v[178:181], v[212:215], v[76:79]
	v_mfma_f32_16x16x32_bf16 v[72:75], v[186:189], v[212:215], v[72:75]
	v_mfma_f32_16x16x32_bf16 v[68:71], v[178:181], v[220:223], v[68:71]
	v_mfma_f32_16x16x32_bf16 v[64:67], v[186:189], v[220:223], v[64:67]
	v_mfma_f32_16x16x32_bf16 v[108:111], v[182:185], v[200:203], v[108:111]
	v_mfma_f32_16x16x32_bf16 v[104:107], v[192:195], v[200:203], v[104:107]
	v_mfma_f32_16x16x32_bf16 v[92:95], v[182:185], v[208:211], v[92:95]
	v_mfma_f32_16x16x32_bf16 v[88:91], v[192:195], v[208:211], v[88:91]
	v_mfma_f32_16x16x32_bf16 v[76:79], v[182:185], v[216:219], v[76:79]
	v_mfma_f32_16x16x32_bf16 v[72:75], v[192:195], v[216:219], v[72:75]
	v_mfma_f32_16x16x32_bf16 v[68:71], v[182:185], v[226:229], v[68:71]
	v_mfma_f32_16x16x32_bf16 v[64:67], v[192:195], v[226:229], v[64:67]
	s_setprio 1
	s_barrier
	s_add_i32 s77, s67, s47
	v_lshl_add_u64 v[230:231], s[30:31], 0, v[134:135]
	s_mov_b32 m0, s77
	ds_read_b128 v[196:199], v160 offset:16384
	ds_read_b128 v[200:203], v160 offset:17408
	ds_read_b128 v[204:207], v160 offset:18432
	ds_read_b128 v[208:211], v160 offset:19456
	ds_read_b128 v[212:215], v160 offset:20480
	ds_read_b128 v[216:219], v160 offset:21504
	ds_read_b128 v[220:223], v160 offset:22528
	ds_read_b128 v[226:229], v160 offset:23552
	global_load_lds_dwordx4 v[230:231], off
	s_add_i32 m0, s77, 0x2000
	s_add_u32 s78, s30, 0x40000
	v_lshl_add_u64 v[232:233], s[30:31], 0, v[132:133]
	s_addc_u32 s79, s31, 0
	s_add_i32 s77, s68, s47
	global_load_lds_dwordx4 v[232:233], off
	v_lshl_add_u64 v[234:235], s[78:79], 0, v[134:135]
	s_mov_b32 m0, s77
	v_lshl_add_u64 v[236:237], s[34:35], 0, v[130:131]
	global_load_lds_dwordx4 v[234:235], off
	v_lshl_add_u64 v[234:235], s[78:79], 0, v[132:133]
	s_add_i32 m0, s77, 0x2000
	s_nop 0
	global_load_lds_dwordx4 v[234:235], off
	v_lshl_add_u64 v[234:235], s[34:35], 0, v[128:129]
	s_mov_b32 m0, s49
	s_nop 0
	global_load_lds_dwordx4 v[234:235], off
	s_mov_b32 m0, s50
	s_nop 0
	global_load_lds_dwordx4 v[236:237], off
	s_waitcnt vmcnt(8)
	s_waitcnt lgkmcnt(0)
	s_barrier
; #define PG8_STAGE(bufoff, gbase, voff) do { _Pragma("unroll") for (int _i = 0; _i < 2; ++_i) \
;         __builtin_amdgcn_global_load_lds((const unsigned*)((const char*)(gbase) + (voff)[_i]), (LAS unsigned*)(lds + (bufoff) + ldsw + _i * 8192), 16, 0, 0); } while (0)
; #define PG8_LDA(dst, b, h) do { _Pragma("unroll") for (int m = 0; m < 4; ++m) _Pragma("unroll") for (int k = 0; k < 2; ++k) dst[m][k] = *(const LAS bf16x8*)(lds + PG8_SA(b, h) + aoff + m * 2048 + k * 1024); } while (0)
; #define PG8_LDB(dst, b, h) do { _Pragma("unroll") for (int n = 0; n < 2; ++n) _Pragma("unroll") for (int k = 0; k < 2; ++k) dst[n][k] = *(const LAS bf16x8*)(lds + PG8_SB(b, h) + boff + n * 2048 + k * 1024); } while (0)
; #define PG8_MMA(ai, bj, At, Bt) do { __builtin_amdgcn_s_setprio(1); _Pragma("unroll") for (int m = 0; m < 4; ++m) _Pragma("unroll") for (int n = 0; n < 2; ++n) _Pragma("unroll") for (int k = 0; k < 2; ++k) \
;         acc[ai][bj][m][n] = __builtin_amdgcn_mfma_f32_16x16x32_bf16(Bt[n][k], At[m][k], acc[ai][bj][m][n], 0, 0, 0); __builtin_amdgcn_s_setprio(0); } while (0)
; #define PG8_WAIT_V(n) asm volatile("s_waitcnt vmcnt(" #n ")" ::: "memory")
; #define PG8_WAIT_L(n) asm volatile("s_waitcnt lgkmcnt(" #n ")" ::: "memory")
; #define PG8_BAR __builtin_amdgcn_s_barrier()
; #define PG8_SCHED __builtin_amdgcn_sched_barrier(0)
; template <class Epi, bool ALIGN_EPI = true, bool SP2 = true>
; DI void gemm_phase(LAS unsigned char* lds, const Gemm g, const StaticOrder& S, const Epi& E) {
;     ...
;             PG8_WAIT_V(8); PG8_WAIT_L(0); PG8_BAR; PG8_MMA(1, 0, At, B0); PG8_MMA(1, 1, At, B1); PG8_BAR; PG8_SCHED;
;             PG8_LDB(B0, 1, 0); PG8_LDB(B1, 1, 1); PG8_SCHED; PG8_LDA(At, 1, 0); PG8_STAGE(PG8_SA(0, 1), a2 + hstepA, voffA);
;             PG8_WAIT_V(8); PG8_WAIT_L(0); PG8_BAR; PG8_MMA(0, 0, At, B0); PG8_MMA(0, 1, At, B1); PG8_BAR; PG8_SCHED;
	s_setprio 0
	s_waitcnt lgkmcnt(0)
	v_mfma_f32_16x16x32_bf16 v[60:63], v[162:165], v[196:199], v[60:63]
	v_mfma_f32_16x16x32_bf16 v[56:59], v[170:173], v[196:199], v[56:59]
	v_mfma_f32_16x16x32_bf16 v[52:55], v[162:165], v[204:207], v[52:55]
	v_mfma_f32_16x16x32_bf16 v[48:51], v[170:173], v[204:207], v[48:51]
	v_mfma_f32_16x16x32_bf16 v[36:39], v[162:165], v[212:215], v[36:39]
	v_mfma_f32_16x16x32_bf16 v[32:35], v[170:173], v[212:215], v[32:35]
	v_mfma_f32_16x16x32_bf16 v[20:23], v[162:165], v[220:223], v[20:23]
	v_mfma_f32_16x16x32_bf16 v[16:19], v[170:173], v[220:223], v[16:19]
	v_mfma_f32_16x16x32_bf16 v[60:63], v[166:169], v[200:203], v[60:63]
	v_mfma_f32_16x16x32_bf16 v[56:59], v[174:177], v[200:203], v[56:59]
	v_mfma_f32_16x16x32_bf16 v[52:55], v[166:169], v[208:211], v[52:55]
	v_mfma_f32_16x16x32_bf16 v[48:51], v[174:177], v[208:211], v[48:51]
	v_mfma_f32_16x16x32_bf16 v[36:39], v[166:169], v[216:219], v[36:39]
	v_mfma_f32_16x16x32_bf16 v[32:35], v[174:177], v[216:219], v[32:35]
	v_mfma_f32_16x16x32_bf16 v[20:23], v[166:169], v[226:229], v[20:23]
	v_mfma_f32_16x16x32_bf16 v[16:19], v[174:177], v[226:229], v[16:19]
	v_mfma_f32_16x16x32_bf16 v[44:47], v[178:181], v[196:199], v[44:47]
	v_mfma_f32_16x16x32_bf16 v[40:43], v[186:189], v[196:199], v[40:43]
	v_mfma_f32_16x16x32_bf16 v[28:31], v[178:181], v[204:207], v[28:31]
	v_mfma_f32_16x16x32_bf16 v[24:27], v[186:189], v[204:207], v[24:27]
	v_mfma_f32_16x16x32_bf16 v[12:15], v[178:181], v[212:215], v[12:15]
	v_mfma_f32_16x16x32_bf16 v[8:11], v[186:189], v[212:215], v[8:11]
	v_mfma_f32_16x16x32_bf16 v[4:7], v[178:181], v[220:223], v[4:7]
	v_mfma_f32_16x16x32_bf16 v[0:3], v[186:189], v[220:223], v[0:3]
	v_mfma_f32_16x16x32_bf16 v[44:47], v[182:185], v[200:203], v[44:47]
	v_mfma_f32_16x16x32_bf16 v[40:43], v[192:195], v[200:203], v[40:43]
	v_mfma_f32_16x16x32_bf16 v[28:31], v[182:185], v[208:211], v[28:31]
	v_mfma_f32_16x16x32_bf16 v[24:27], v[192:195], v[208:211], v[24:27]
	v_mfma_f32_16x16x32_bf16 v[12:15], v[182:185], v[216:219], v[12:15]
	v_mfma_f32_16x16x32_bf16 v[8:11], v[192:195], v[216:219], v[8:11]
	v_mfma_f32_16x16x32_bf16 v[4:7], v[182:185], v[226:229], v[4:7]
	v_mfma_f32_16x16x32_bf16 v[0:3], v[192:195], v[226:229], v[0:3]
	s_setprio 1
	s_barrier
	s_add_i32 s77, 0, 0x18000
	v_add_u32_e32 v161, s77, v156
	s_add_i32 s78, 0, 0x1c000
	ds_read_b128 v[162:165], v161
	ds_read_b128 v[166:169], v161 offset:1024
	ds_read_b128 v[170:173], v161 offset:2048
	ds_read_b128 v[174:177], v161 offset:3072
	v_add_u32_e32 v161, s78, v156
	ds_read_b128 v[178:181], v161
	ds_read_b128 v[182:185], v161 offset:1024
	ds_read_b128 v[186:189], v161 offset:2048
	ds_read_b128 v[192:195], v161 offset:3072
	s_add_u32 s34, s34, 0x480000
	s_addc_u32 s35, s35, 0
	s_mov_b32 m0, s51
	v_lshl_add_u64 v[238:239], s[34:35], 0, v[128:129]
	ds_read_b128 v[196:199], v160 offset:32768
	ds_read_b128 v[200:203], v160 offset:33792
	ds_read_b128 v[204:207], v160 offset:34816
	ds_read_b128 v[208:211], v160 offset:35840
	ds_read_b128 v[212:215], v160 offset:36864
	ds_read_b128 v[216:219], v160 offset:37888
	ds_read_b128 v[220:223], v160 offset:38912
	ds_read_b128 v[226:229], v160 offset:39936
	global_load_lds_dwordx4 v[238:239], off
	v_lshl_add_u64 v[238:239], s[34:35], 0, v[130:131]
	s_mov_b32 m0, s60
	s_nop 0
	global_load_lds_dwordx4 v[238:239], off
	s_waitcnt vmcnt(8)
	s_waitcnt lgkmcnt(0)
	s_barrier
	s_setprio 0
	s_waitcnt lgkmcnt(0)
	v_mfma_f32_16x16x32_bf16 v[124:127], v[162:165], v[196:199], v[124:127]
	v_mfma_f32_16x16x32_bf16 v[120:123], v[170:173], v[196:199], v[120:123]
	v_mfma_f32_16x16x32_bf16 v[116:119], v[162:165], v[204:207], v[116:119]
	v_mfma_f32_16x16x32_bf16 v[112:115], v[170:173], v[204:207], v[112:115]
	v_mfma_f32_16x16x32_bf16 v[100:103], v[162:165], v[212:215], v[100:103]
	v_mfma_f32_16x16x32_bf16 v[96:99], v[170:173], v[212:215], v[96:99]
	v_mfma_f32_16x16x32_bf16 v[84:87], v[162:165], v[220:223], v[84:87]
	v_mfma_f32_16x16x32_bf16 v[80:83], v[170:173], v[220:223], v[80:83]
	v_mfma_f32_16x16x32_bf16 v[124:127], v[166:169], v[200:203], v[124:127]
	v_mfma_f32_16x16x32_bf16 v[120:123], v[174:177], v[200:203], v[120:123]
	v_mfma_f32_16x16x32_bf16 v[116:119], v[166:169], v[208:211], v[116:119]
	v_mfma_f32_16x16x32_bf16 v[112:115], v[174:177], v[208:211], v[112:115]
	v_mfma_f32_16x16x32_bf16 v[100:103], v[166:169], v[216:219], v[100:103]
	v_mfma_f32_16x16x32_bf16 v[96:99], v[174:177], v[216:219], v[96:99]
	v_mfma_f32_16x16x32_bf16 v[84:87], v[166:169], v[226:229], v[84:87]
	v_mfma_f32_16x16x32_bf16 v[80:83], v[174:177], v[226:229], v[80:83]
	v_mfma_f32_16x16x32_bf16 v[108:111], v[178:181], v[196:199], v[108:111]
	v_mfma_f32_16x16x32_bf16 v[104:107], v[186:189], v[196:199], v[104:107]
	v_mfma_f32_16x16x32_bf16 v[92:95], v[178:181], v[204:207], v[92:95]
	v_mfma_f32_16x16x32_bf16 v[88:91], v[186:189], v[204:207], v[88:91]
	v_mfma_f32_16x16x32_bf16 v[76:79], v[178:181], v[212:215], v[76:79]
	v_mfma_f32_16x16x32_bf16 v[72:75], v[186:189], v[212:215], v[72:75]
	v_mfma_f32_16x16x32_bf16 v[68:71], v[178:181], v[220:223], v[68:71]
	v_mfma_f32_16x16x32_bf16 v[64:67], v[186:189], v[220:223], v[64:67]
	v_mfma_f32_16x16x32_bf16 v[108:111], v[182:185], v[200:203], v[108:111]
	v_mfma_f32_16x16x32_bf16 v[104:107], v[192:195], v[200:203], v[104:107]
	v_mfma_f32_16x16x32_bf16 v[92:95], v[182:185], v[208:211], v[92:95]
	v_mfma_f32_16x16x32_bf16 v[88:91], v[192:195], v[208:211], v[88:91]
	v_mfma_f32_16x16x32_bf16 v[76:79], v[182:185], v[216:219], v[76:79]
	v_mfma_f32_16x16x32_bf16 v[72:75], v[192:195], v[216:219], v[72:75]
	v_mfma_f32_16x16x32_bf16 v[68:71], v[182:185], v[226:229], v[68:71]
	v_mfma_f32_16x16x32_bf16 v[64:67], v[192:195], v[226:229], v[64:67]
	s_setprio 1
	s_barrier
; #define PG8_STAGE(bufoff, gbase, voff) do { _Pragma("unroll") for (int _i = 0; _i < 2; ++_i) \
;         __builtin_amdgcn_global_load_lds((const unsigned*)((const char*)(gbase) + (voff)[_i]), (LAS unsigned*)(lds + (bufoff) + ldsw + _i * 8192), 16, 0, 0); } while (0)
; #define PG8_LDA(dst, b, h) do { _Pragma("unroll") for (int m = 0; m < 4; ++m) _Pragma("unroll") for (int k = 0; k < 2; ++k) dst[m][k] = *(const LAS bf16x8*)(lds + PG8_SA(b, h) + aoff + m * 2048 + k * 1024); } while (0)
; #define PG8_MMA(ai, bj, At, Bt) do { __builtin_amdgcn_s_setprio(1); _Pragma("unroll") for (int m = 0; m < 4; ++m) _Pragma("unroll") for (int n = 0; n < 2; ++n) _Pragma("unroll") for (int k = 0; k < 2; ++k) \
;         acc[ai][bj][m][n] = __builtin_amdgcn_mfma_f32_16x16x32_bf16(Bt[n][k], At[m][k], acc[ai][bj][m][n], 0, 0, 0); __builtin_amdgcn_s_setprio(0); } while (0)
; #define PG8_WAIT_V(n) asm volatile("s_waitcnt vmcnt(" #n ")" ::: "memory")
; #define PG8_WAIT_L(n) asm volatile("s_waitcnt lgkmcnt(" #n ")" ::: "memory")
; #define PG8_BAR __builtin_amdgcn_s_barrier()
; #define PG8_SCHED __builtin_amdgcn_sched_barrier(0)
; template <class Epi, bool ALIGN_EPI = true, bool SP2 = true>
; DI void gemm_phase(LAS unsigned char* lds, const Gemm g, const StaticOrder& S, const Epi& E) {
;     ...
;             PG8_LDA(At, 1, 1); PG8_STAGE(PG8_SB(1, 0), b3, voffB); PG8_STAGE(PG8_SB(1, 1), b3 + hstepB, voffB); PG8_STAGE(PG8_SA(1, 0), a3, voffA);
;             PG8_WAIT_V(8); PG8_WAIT_L(0); PG8_BAR; PG8_MMA(1, 0, At, B0); PG8_MMA(1, 1, At, B1); PG8_BAR; PG8_SCHED;
;     ...
;         if constexpr (ALIGN_EPI) { if (wr == 0) PG8_BAR; }
	s_add_i32 s34, s77, s47
	v_lshl_add_u64 v[230:231], v[230:231], 0, s[18:19]
	s_mov_b32 m0, s34
	ds_read_b128 v[196:199], v160 offset:49152
	ds_read_b128 v[200:203], v160 offset:50176
	ds_read_b128 v[204:207], v160 offset:51200
	ds_read_b128 v[208:211], v160 offset:52224
	ds_read_b128 v[212:215], v160 offset:53248
	ds_read_b128 v[216:219], v160 offset:54272
	ds_read_b128 v[220:223], v160 offset:55296
	ds_read_b128 v[226:229], v160 offset:56320
	global_load_lds_dwordx4 v[230:231], off
	s_add_i32 m0, s34, 0x2000
	s_add_u32 s30, s30, 0x40080
	v_lshl_add_u64 v[230:231], v[232:233], 0, s[18:19]
	s_addc_u32 s31, s31, 0
	s_add_i32 s34, s78, s47
	global_load_lds_dwordx4 v[230:231], off
	v_lshl_add_u64 v[230:231], s[30:31], 0, v[134:135]
	s_mov_b32 m0, s34
	s_nop 0
	global_load_lds_dwordx4 v[230:231], off
	v_lshl_add_u64 v[230:231], s[30:31], 0, v[132:133]
	s_add_i32 m0, s34, 0x2000
	s_nop 0
	global_load_lds_dwordx4 v[230:231], off
	v_lshl_add_u64 v[230:231], v[234:235], 0, s[18:19]
	s_mov_b32 m0, s62
	s_nop 0
	global_load_lds_dwordx4 v[230:231], off
	v_lshl_add_u64 v[230:231], v[236:237], 0, s[18:19]
	s_mov_b32 m0, s63
	s_nop 0
	global_load_lds_dwordx4 v[230:231], off
	s_waitcnt vmcnt(8)
	s_waitcnt lgkmcnt(0)
	s_barrier
	s_setprio 0
	s_waitcnt lgkmcnt(0)
	v_mfma_f32_16x16x32_bf16 v[60:63], v[162:165], v[196:199], v[60:63]
	v_mfma_f32_16x16x32_bf16 v[56:59], v[170:173], v[196:199], v[56:59]
	v_mfma_f32_16x16x32_bf16 v[52:55], v[162:165], v[204:207], v[52:55]
	v_mfma_f32_16x16x32_bf16 v[48:51], v[170:173], v[204:207], v[48:51]
	v_mfma_f32_16x16x32_bf16 v[36:39], v[162:165], v[212:215], v[36:39]
	v_mfma_f32_16x16x32_bf16 v[32:35], v[170:173], v[212:215], v[32:35]
	v_mfma_f32_16x16x32_bf16 v[20:23], v[162:165], v[220:223], v[20:23]
	v_mfma_f32_16x16x32_bf16 v[16:19], v[170:173], v[220:223], v[16:19]
	v_mfma_f32_16x16x32_bf16 v[60:63], v[166:169], v[200:203], v[60:63]
	v_mfma_f32_16x16x32_bf16 v[56:59], v[174:177], v[200:203], v[56:59]
	v_mfma_f32_16x16x32_bf16 v[52:55], v[166:169], v[208:211], v[52:55]
	v_mfma_f32_16x16x32_bf16 v[48:51], v[174:177], v[208:211], v[48:51]
	v_mfma_f32_16x16x32_bf16 v[36:39], v[166:169], v[216:219], v[36:39]
	v_mfma_f32_16x16x32_bf16 v[32:35], v[174:177], v[216:219], v[32:35]
	v_mfma_f32_16x16x32_bf16 v[20:23], v[166:169], v[226:229], v[20:23]
	v_mfma_f32_16x16x32_bf16 v[16:19], v[174:177], v[226:229], v[16:19]
	v_mfma_f32_16x16x32_bf16 v[44:47], v[178:181], v[196:199], v[44:47]
	v_mfma_f32_16x16x32_bf16 v[40:43], v[186:189], v[196:199], v[40:43]
	v_mfma_f32_16x16x32_bf16 v[28:31], v[178:181], v[204:207], v[28:31]
	v_mfma_f32_16x16x32_bf16 v[24:27], v[186:189], v[204:207], v[24:27]
	v_mfma_f32_16x16x32_bf16 v[12:15], v[178:181], v[212:215], v[12:15]
	v_mfma_f32_16x16x32_bf16 v[8:11], v[186:189], v[212:215], v[8:11]
	v_mfma_f32_16x16x32_bf16 v[4:7], v[178:181], v[220:223], v[4:7]
	v_mfma_f32_16x16x32_bf16 v[0:3], v[186:189], v[220:223], v[0:3]
	v_mfma_f32_16x16x32_bf16 v[44:47], v[182:185], v[200:203], v[44:47]
	v_mfma_f32_16x16x32_bf16 v[40:43], v[192:195], v[200:203], v[40:43]
	v_mfma_f32_16x16x32_bf16 v[28:31], v[182:185], v[208:211], v[28:31]
	v_mfma_f32_16x16x32_bf16 v[24:27], v[192:195], v[208:211], v[24:27]
	v_mfma_f32_16x16x32_bf16 v[12:15], v[182:185], v[216:219], v[12:15]
	v_mfma_f32_16x16x32_bf16 v[8:11], v[192:195], v[216:219], v[8:11]
	v_mfma_f32_16x16x32_bf16 v[4:7], v[182:185], v[226:229], v[4:7]
	v_mfma_f32_16x16x32_bf16 v[0:3], v[192:195], v[226:229], v[0:3]
	s_setprio 1
	s_barrier
	s_add_i32 s76, s76, 2
	s_add_u32 s0, s0, 0x100
	s_addc_u32 s1, s1, 0
	s_add_u32 s74, s74, 0x100
	s_addc_u32 s75, s75, 0
	s_cmp_gt_u32 s76, 13
	s_cbranch_scc0 .LBB0_334
	s_and_b64 vcc, exec, s[20:21]
	s_cbranch_vccz .LBB0_337
	s_barrier

; #define PG8_STAGE(bufoff, gbase, voff) do { _Pragma("unroll") for (int _i = 0; _i < 2; ++_i) \
;         __builtin_amdgcn_global_load_lds((const unsigned*)((const char*)(gbase) + (voff)[_i]), (LAS unsigned*)(lds + (bufoff) + ldsw + _i * 8192), 16, 0, 0); } while (0)
; #define PG8_LDA(dst, b, h) do { _Pragma("unroll") for (int m = 0; m < 4; ++m) _Pragma("unroll") for (int k = 0; k < 2; ++k) dst[m][k] = *(const LAS bf16x8*)(lds + PG8_SA(b, h) + aoff + m * 2048 + k * 1024); } while (0)
; #define PG8_LDB(dst, b, h) do { _Pragma("unroll") for (int n = 0; n < 2; ++n) _Pragma("unroll") for (int k = 0; k < 2; ++k) dst[n][k] = *(const LAS bf16x8*)(lds + PG8_SB(b, h) + boff + n * 2048 + k * 1024); } while (0)
; #define PG8_MMA(ai, bj, At, Bt) do { __builtin_amdgcn_s_setprio(1); _Pragma("unroll") for (int m = 0; m < 4; ++m) _Pragma("unroll") for (int n = 0; n < 2; ++n) _Pragma("unroll") for (int k = 0; k < 2; ++k) \
;         acc[ai][bj][m][n] = __builtin_amdgcn_mfma_f32_16x16x32_bf16(Bt[n][k], At[m][k], acc[ai][bj][m][n], 0, 0, 0); __builtin_amdgcn_s_setprio(0); } while (0)
; #define PG8_BAR __builtin_amdgcn_s_barrier()
; template <class Epi, bool ALIGN_EPI = true, bool SP2 = true>
; DI void gemm_phase(LAS unsigned char* lds, const Gemm g, const StaticOrder& S, const Epi& E) {
;     ...
;             const bool last = (t == nt - 2);
;             const char* a1 = cA + (size_t)(t + 1) * kstep;
;             const char* a2 = last ? nA : cA + (size_t)(t + 2) * kstep; const char* b2 = last ? nB : cB + (size_t)(t + 2) * kstep;
;             const char* a3 = a2 + kstep; const char* b3 = b2 + kstep;
;             if (Epi::MID) { if (t == (nt >> 1)) {
;                 if constexpr (ALIGN_EPI) { if (wr == 0) PG8_BAR; }
;                 E.mid(acc, cur, wr, wc, fr, fq);
;                 if constexpr (ALIGN_EPI) { if (wr == 1) PG8_BAR; } } }
;             if constexpr (SP2) {
;             PG8_LDB(B0, 0, 0); PG8_LDB(B1, 0, 1); PG8_SCHED; PG8_LDA(At, 0, 0); PG8_STAGE(PG8_SA(1, 1), a1 + hstepA, voffA);
;             PG8_WAIT_V(8); PG8_WAIT_L(0); PG8_BAR; PG8_MMA(0, 0, At, B0); PG8_MMA(0, 1, At, B1); PG8_BAR; PG8_SCHED;
;             PG8_LDA(At, 0, 1); PG8_STAGE(PG8_SB(0, 0), b2, voffB); PG8_STAGE(PG8_SB(0, 1), b2 + hstepB, voffB); PG8_STAGE(PG8_SA(0, 0), a2, voffA);
;             PG8_WAIT_V(8); PG8_WAIT_L(0); PG8_BAR; PG8_MMA(1, 0, At, B0); PG8_MMA(1, 1, At, B1); PG8_BAR; PG8_SCHED;
.LBB0_360:
	ds_read_b128 v[154:157], v144
	ds_read_b128 v[158:161], v144 offset:1024
	ds_read_b128 v[162:165], v144 offset:2048
	ds_read_b128 v[166:169], v144 offset:3072
	ds_read_b128 v[170:173], v145
	ds_read_b128 v[174:177], v145 offset:1024
	ds_read_b128 v[178:181], v145 offset:2048
	ds_read_b128 v[182:185], v145 offset:3072
	s_add_u32 s60, s0, 0xffb80080
	s_addc_u32 s61, s1, -1
	s_cmp_eq_u32 s90, 4
	s_cselect_b32 s63, s49, s61
	s_cselect_b32 s62, s48, s60
	s_cselect_b32 s61, s47, s89
	s_cselect_b32 s60, s87, s88
	v_lshl_add_u64 v[150:151], s[0:1], 0, v[136:137]
	s_add_i32 m0, s69, 0xc000
	ds_read_b128 v[186:189], v148
	ds_read_b128 v[192:195], v148 offset:1024
	ds_read_b128 v[196:199], v148 offset:2048
	ds_read_b128 v[200:203], v148 offset:3072
	ds_read_b128 v[204:207], v148 offset:4096
	ds_read_b128 v[208:211], v148 offset:5120
	ds_read_b128 v[212:215], v148 offset:6144
	ds_read_b128 v[216:219], v148 offset:7168
	global_load_lds_dwordx4 v[150:151], off
	v_lshl_add_u64 v[150:151], s[0:1], 0, v[138:139]
	s_add_i32 m0, s69, 0xe000
	s_nop 0
	global_load_lds_dwordx4 v[150:151], off
	s_waitcnt vmcnt(8)
	s_waitcnt lgkmcnt(0)
	s_barrier
	s_setprio 0
	s_waitcnt lgkmcnt(0)
	v_mfma_f32_16x16x32_bf16 v[124:127], v[154:157], v[186:189], v[124:127]
	v_mfma_f32_16x16x32_bf16 v[120:123], v[162:165], v[186:189], v[120:123]
	v_mfma_f32_16x16x32_bf16 v[116:119], v[154:157], v[196:199], v[116:119]
	v_mfma_f32_16x16x32_bf16 v[112:115], v[162:165], v[196:199], v[112:115]
	v_mfma_f32_16x16x32_bf16 v[100:103], v[154:157], v[204:207], v[100:103]
	v_mfma_f32_16x16x32_bf16 v[96:99], v[162:165], v[204:207], v[96:99]
	v_mfma_f32_16x16x32_bf16 v[84:87], v[154:157], v[212:215], v[84:87]
	v_mfma_f32_16x16x32_bf16 v[80:83], v[162:165], v[212:215], v[80:83]
	v_mfma_f32_16x16x32_bf16 v[124:127], v[158:161], v[192:195], v[124:127]
	v_mfma_f32_16x16x32_bf16 v[120:123], v[166:169], v[192:195], v[120:123]
	v_mfma_f32_16x16x32_bf16 v[116:119], v[158:161], v[200:203], v[116:119]
	v_mfma_f32_16x16x32_bf16 v[112:115], v[166:169], v[200:203], v[112:115]
	v_mfma_f32_16x16x32_bf16 v[100:103], v[158:161], v[208:211], v[100:103]
	v_mfma_f32_16x16x32_bf16 v[96:99], v[166:169], v[208:211], v[96:99]
	v_mfma_f32_16x16x32_bf16 v[84:87], v[158:161], v[216:219], v[84:87]
	v_mfma_f32_16x16x32_bf16 v[80:83], v[166:169], v[216:219], v[80:83]
	v_mfma_f32_16x16x32_bf16 v[108:111], v[170:173], v[186:189], v[108:111]
	v_mfma_f32_16x16x32_bf16 v[104:107], v[178:181], v[186:189], v[104:107]
	v_mfma_f32_16x16x32_bf16 v[92:95], v[170:173], v[196:199], v[92:95]
	v_mfma_f32_16x16x32_bf16 v[88:91], v[178:181], v[196:199], v[88:91]
	v_mfma_f32_16x16x32_bf16 v[76:79], v[170:173], v[204:207], v[76:79]
	v_mfma_f32_16x16x32_bf16 v[72:75], v[178:181], v[204:207], v[72:75]
	v_mfma_f32_16x16x32_bf16 v[68:71], v[170:173], v[212:215], v[68:71]
	v_mfma_f32_16x16x32_bf16 v[64:67], v[178:181], v[212:215], v[64:67]
	v_mfma_f32_16x16x32_bf16 v[108:111], v[174:177], v[192:195], v[108:111]
	v_mfma_f32_16x16x32_bf16 v[104:107], v[182:185], v[192:195], v[104:107]
	v_mfma_f32_16x16x32_bf16 v[92:95], v[174:177], v[200:203], v[92:95]
	v_mfma_f32_16x16x32_bf16 v[88:91], v[182:185], v[200:203], v[88:91]
	v_mfma_f32_16x16x32_bf16 v[76:79], v[174:177], v[208:211], v[76:79]
	v_mfma_f32_16x16x32_bf16 v[72:75], v[182:185], v[208:211], v[72:75]
	v_mfma_f32_16x16x32_bf16 v[68:71], v[174:177], v[216:219], v[68:71]
	v_mfma_f32_16x16x32_bf16 v[64:67], v[182:185], v[216:219], v[64:67]
	s_setprio 1
	s_barrier
	s_add_i32 s91, s78, s68
	v_lshl_add_u64 v[150:151], s[60:61], 0, v[132:133]
	s_mov_b32 m0, s91
	ds_read_b128 v[186:189], v148 offset:16384
	ds_read_b128 v[192:195], v148 offset:17408
	ds_read_b128 v[196:199], v148 offset:18432
	ds_read_b128 v[200:203], v148 offset:19456
	ds_read_b128 v[204:207], v148 offset:20480
	ds_read_b128 v[208:211], v148 offset:21504
	ds_read_b128 v[212:215], v148 offset:22528
	ds_read_b128 v[216:219], v148 offset:23552
	global_load_lds_dwordx4 v[150:151], off
	s_add_i32 m0, s91, 0x2000
	s_add_u32 s92, s60, 0x20000
	v_lshl_add_u64 v[220:221], s[60:61], 0, v[134:135]
	s_addc_u32 s93, s61, 0
	s_add_i32 s91, s79, s68
	global_load_lds_dwordx4 v[220:221], off
	v_lshl_add_u64 v[222:223], s[92:93], 0, v[132:133]
	s_mov_b32 m0, s91
	v_lshl_add_u64 v[226:227], s[62:63], 0, v[130:131]
	global_load_lds_dwordx4 v[222:223], off
	v_lshl_add_u64 v[222:223], s[92:93], 0, v[134:135]
	s_add_i32 m0, s91, 0x2000
	s_nop 0
	global_load_lds_dwordx4 v[222:223], off
	v_lshl_add_u64 v[222:223], s[62:63], 0, v[128:129]
	s_mov_b32 m0, s69
	s_nop 0
	global_load_lds_dwordx4 v[222:223], off
	s_mov_b32 m0, s70
	s_nop 0
	global_load_lds_dwordx4 v[226:227], off
	s_waitcnt vmcnt(8)
	s_waitcnt lgkmcnt(0)
	s_barrier
; #define PG8_STAGE(bufoff, gbase, voff) do { _Pragma("unroll") for (int _i = 0; _i < 2; ++_i) \
;         __builtin_amdgcn_global_load_lds((const unsigned*)((const char*)(gbase) + (voff)[_i]), (LAS unsigned*)(lds + (bufoff) + ldsw + _i * 8192), 16, 0, 0); } while (0)
; #define PG8_LDA(dst, b, h) do { _Pragma("unroll") for (int m = 0; m < 4; ++m) _Pragma("unroll") for (int k = 0; k < 2; ++k) dst[m][k] = *(const LAS bf16x8*)(lds + PG8_SA(b, h) + aoff + m * 2048 + k * 1024); } while (0)
; #define PG8_LDB(dst, b, h) do { _Pragma("unroll") for (int n = 0; n < 2; ++n) _Pragma("unroll") for (int k = 0; k < 2; ++k) dst[n][k] = *(const LAS bf16x8*)(lds + PG8_SB(b, h) + boff + n * 2048 + k * 1024); } while (0)
; #define PG8_MMA(ai, bj, At, Bt) do { __builtin_amdgcn_s_setprio(1); _Pragma("unroll") for (int m = 0; m < 4; ++m) _Pragma("unroll") for (int n = 0; n < 2; ++n) _Pragma("unroll") for (int k = 0; k < 2; ++k) \
;         acc[ai][bj][m][n] = __builtin_amdgcn_mfma_f32_16x16x32_bf16(Bt[n][k], At[m][k], acc[ai][bj][m][n], 0, 0, 0); __builtin_amdgcn_s_setprio(0); } while (0)
; #define PG8_WAIT_V(n) asm volatile("s_waitcnt vmcnt(" #n ")" ::: "memory")
; #define PG8_WAIT_L(n) asm volatile("s_waitcnt lgkmcnt(" #n ")" ::: "memory")
; #define PG8_BAR __builtin_amdgcn_s_barrier()
; #define PG8_SCHED __builtin_amdgcn_sched_barrier(0)
; template <class Epi, bool ALIGN_EPI = true, bool SP2 = true>
; DI void gemm_phase(LAS unsigned char* lds, const Gemm g, const StaticOrder& S, const Epi& E) {
;     ...
;             PG8_WAIT_V(8); PG8_WAIT_L(0); PG8_BAR; PG8_MMA(1, 0, At, B0); PG8_MMA(1, 1, At, B1); PG8_BAR; PG8_SCHED;
;             PG8_LDB(B0, 1, 0); PG8_LDB(B1, 1, 1); PG8_SCHED; PG8_LDA(At, 1, 0); PG8_STAGE(PG8_SA(0, 1), a2 + hstepA, voffA);
;             PG8_WAIT_V(8); PG8_WAIT_L(0); PG8_BAR; PG8_MMA(0, 0, At, B0); PG8_MMA(0, 1, At, B1); PG8_BAR; PG8_SCHED;
	s_setprio 0
	s_waitcnt lgkmcnt(0)
	v_mfma_f32_16x16x32_bf16 v[60:63], v[154:157], v[186:189], v[60:63]
	v_mfma_f32_16x16x32_bf16 v[56:59], v[162:165], v[186:189], v[56:59]
	v_mfma_f32_16x16x32_bf16 v[52:55], v[154:157], v[196:199], v[52:55]
	v_mfma_f32_16x16x32_bf16 v[48:51], v[162:165], v[196:199], v[48:51]
	v_mfma_f32_16x16x32_bf16 v[36:39], v[154:157], v[204:207], v[36:39]
	v_mfma_f32_16x16x32_bf16 v[32:35], v[162:165], v[204:207], v[32:35]
	v_mfma_f32_16x16x32_bf16 v[20:23], v[154:157], v[212:215], v[20:23]
	v_mfma_f32_16x16x32_bf16 v[16:19], v[162:165], v[212:215], v[16:19]
	v_mfma_f32_16x16x32_bf16 v[60:63], v[158:161], v[192:195], v[60:63]
	v_mfma_f32_16x16x32_bf16 v[56:59], v[166:169], v[192:195], v[56:59]
	v_mfma_f32_16x16x32_bf16 v[52:55], v[158:161], v[200:203], v[52:55]
	v_mfma_f32_16x16x32_bf16 v[48:51], v[166:169], v[200:203], v[48:51]
	v_mfma_f32_16x16x32_bf16 v[36:39], v[158:161], v[208:211], v[36:39]
	v_mfma_f32_16x16x32_bf16 v[32:35], v[166:169], v[208:211], v[32:35]
	v_mfma_f32_16x16x32_bf16 v[20:23], v[158:161], v[216:219], v[20:23]
	v_mfma_f32_16x16x32_bf16 v[16:19], v[166:169], v[216:219], v[16:19]
	v_mfma_f32_16x16x32_bf16 v[44:47], v[170:173], v[186:189], v[44:47]
	v_mfma_f32_16x16x32_bf16 v[40:43], v[178:181], v[186:189], v[40:43]
	v_mfma_f32_16x16x32_bf16 v[28:31], v[170:173], v[196:199], v[28:31]
	v_mfma_f32_16x16x32_bf16 v[24:27], v[178:181], v[196:199], v[24:27]
	v_mfma_f32_16x16x32_bf16 v[12:15], v[170:173], v[204:207], v[12:15]
	v_mfma_f32_16x16x32_bf16 v[8:11], v[178:181], v[204:207], v[8:11]
	v_mfma_f32_16x16x32_bf16 v[4:7], v[170:173], v[212:215], v[4:7]
	v_mfma_f32_16x16x32_bf16 v[0:3], v[178:181], v[212:215], v[0:3]
	v_mfma_f32_16x16x32_bf16 v[44:47], v[174:177], v[192:195], v[44:47]
	v_mfma_f32_16x16x32_bf16 v[40:43], v[182:185], v[192:195], v[40:43]
	v_mfma_f32_16x16x32_bf16 v[28:31], v[174:177], v[200:203], v[28:31]
	v_mfma_f32_16x16x32_bf16 v[24:27], v[182:185], v[200:203], v[24:27]
	v_mfma_f32_16x16x32_bf16 v[12:15], v[174:177], v[208:211], v[12:15]
	v_mfma_f32_16x16x32_bf16 v[8:11], v[182:185], v[208:211], v[8:11]
	v_mfma_f32_16x16x32_bf16 v[4:7], v[174:177], v[216:219], v[4:7]
	v_mfma_f32_16x16x32_bf16 v[0:3], v[182:185], v[216:219], v[0:3]
	s_setprio 1
	s_barrier
	s_add_i32 s91, 0, 0x18000
	v_add_u32_e32 v149, s91, v147
	s_add_i32 s92, 0, 0x1c000
	ds_read_b128 v[154:157], v149
	ds_read_b128 v[158:161], v149 offset:1024
	ds_read_b128 v[162:165], v149 offset:2048
	ds_read_b128 v[166:169], v149 offset:3072
	v_add_u32_e32 v149, s92, v147
	ds_read_b128 v[170:173], v149
	ds_read_b128 v[174:177], v149 offset:1024
	ds_read_b128 v[178:181], v149 offset:2048
	ds_read_b128 v[182:185], v149 offset:3072
	s_add_u32 s62, s62, 0x480000
	s_addc_u32 s63, s63, 0
	s_mov_b32 m0, s71
	v_lshl_add_u64 v[228:229], s[62:63], 0, v[128:129]
	ds_read_b128 v[186:189], v148 offset:32768
	ds_read_b128 v[192:195], v148 offset:33792
	ds_read_b128 v[196:199], v148 offset:34816
	ds_read_b128 v[200:203], v148 offset:35840
	ds_read_b128 v[204:207], v148 offset:36864
	ds_read_b128 v[208:211], v148 offset:37888
	ds_read_b128 v[212:215], v148 offset:38912
	ds_read_b128 v[216:219], v148 offset:39936
	global_load_lds_dwordx4 v[228:229], off
	v_lshl_add_u64 v[228:229], s[62:63], 0, v[130:131]
	s_mov_b32 m0, s72
	s_nop 0
	global_load_lds_dwordx4 v[228:229], off
	s_waitcnt vmcnt(8)
	s_waitcnt lgkmcnt(0)
	s_barrier
	s_setprio 0
	s_waitcnt lgkmcnt(0)
	v_mfma_f32_16x16x32_bf16 v[124:127], v[154:157], v[186:189], v[124:127]
	v_mfma_f32_16x16x32_bf16 v[120:123], v[162:165], v[186:189], v[120:123]
	v_mfma_f32_16x16x32_bf16 v[116:119], v[154:157], v[196:199], v[116:119]
	v_mfma_f32_16x16x32_bf16 v[112:115], v[162:165], v[196:199], v[112:115]
	v_mfma_f32_16x16x32_bf16 v[100:103], v[154:157], v[204:207], v[100:103]
	v_mfma_f32_16x16x32_bf16 v[96:99], v[162:165], v[204:207], v[96:99]
	v_mfma_f32_16x16x32_bf16 v[84:87], v[154:157], v[212:215], v[84:87]
	v_mfma_f32_16x16x32_bf16 v[80:83], v[162:165], v[212:215], v[80:83]
	v_mfma_f32_16x16x32_bf16 v[124:127], v[158:161], v[192:195], v[124:127]
	v_mfma_f32_16x16x32_bf16 v[120:123], v[166:169], v[192:195], v[120:123]
	v_mfma_f32_16x16x32_bf16 v[116:119], v[158:161], v[200:203], v[116:119]
	v_mfma_f32_16x16x32_bf16 v[112:115], v[166:169], v[200:203], v[112:115]
	v_mfma_f32_16x16x32_bf16 v[100:103], v[158:161], v[208:211], v[100:103]
	v_mfma_f32_16x16x32_bf16 v[96:99], v[166:169], v[208:211], v[96:99]
	v_mfma_f32_16x16x32_bf16 v[84:87], v[158:161], v[216:219], v[84:87]
	v_mfma_f32_16x16x32_bf16 v[80:83], v[166:169], v[216:219], v[80:83]
	v_mfma_f32_16x16x32_bf16 v[108:111], v[170:173], v[186:189], v[108:111]
	v_mfma_f32_16x16x32_bf16 v[104:107], v[178:181], v[186:189], v[104:107]
	v_mfma_f32_16x16x32_bf16 v[92:95], v[170:173], v[196:199], v[92:95]
	v_mfma_f32_16x16x32_bf16 v[88:91], v[178:181], v[196:199], v[88:91]
	v_mfma_f32_16x16x32_bf16 v[76:79], v[170:173], v[204:207], v[76:79]
	v_mfma_f32_16x16x32_bf16 v[72:75], v[178:181], v[204:207], v[72:75]
	v_mfma_f32_16x16x32_bf16 v[68:71], v[170:173], v[212:215], v[68:71]
	v_mfma_f32_16x16x32_bf16 v[64:67], v[178:181], v[212:215], v[64:67]
	v_mfma_f32_16x16x32_bf16 v[108:111], v[174:177], v[192:195], v[108:111]
	v_mfma_f32_16x16x32_bf16 v[104:107], v[182:185], v[192:195], v[104:107]
	v_mfma_f32_16x16x32_bf16 v[92:95], v[174:177], v[200:203], v[92:95]
	v_mfma_f32_16x16x32_bf16 v[88:91], v[182:185], v[200:203], v[88:91]
	v_mfma_f32_16x16x32_bf16 v[76:79], v[174:177], v[208:211], v[76:79]
	v_mfma_f32_16x16x32_bf16 v[72:75], v[182:185], v[208:211], v[72:75]
	v_mfma_f32_16x16x32_bf16 v[68:71], v[174:177], v[216:219], v[68:71]
	v_mfma_f32_16x16x32_bf16 v[64:67], v[182:185], v[216:219], v[64:67]
	s_setprio 1
	s_barrier
; #define PG8_STAGE(bufoff, gbase, voff) do { _Pragma("unroll") for (int _i = 0; _i < 2; ++_i) \
;         __builtin_amdgcn_global_load_lds((const unsigned*)((const char*)(gbase) + (voff)[_i]), (LAS unsigned*)(lds + (bufoff) + ldsw + _i * 8192), 16, 0, 0); } while (0)
; #define PG8_LDA(dst, b, h) do { _Pragma("unroll") for (int m = 0; m < 4; ++m) _Pragma("unroll") for (int k = 0; k < 2; ++k) dst[m][k] = *(const LAS bf16x8*)(lds + PG8_SA(b, h) + aoff + m * 2048 + k * 1024); } while (0)
; #define PG8_MMA(ai, bj, At, Bt) do { __builtin_amdgcn_s_setprio(1); _Pragma("unroll") for (int m = 0; m < 4; ++m) _Pragma("unroll") for (int n = 0; n < 2; ++n) _Pragma("unroll") for (int k = 0; k < 2; ++k) \
;         acc[ai][bj][m][n] = __builtin_amdgcn_mfma_f32_16x16x32_bf16(Bt[n][k], At[m][k], acc[ai][bj][m][n], 0, 0, 0); __builtin_amdgcn_s_setprio(0); } while (0)
; #define PG8_WAIT_V(n) asm volatile("s_waitcnt vmcnt(" #n ")" ::: "memory")
; #define PG8_WAIT_L(n) asm volatile("s_waitcnt lgkmcnt(" #n ")" ::: "memory")
; #define PG8_BAR __builtin_amdgcn_s_barrier()
; #define PG8_SCHED __builtin_amdgcn_sched_barrier(0)
; template <class Epi, bool ALIGN_EPI = true, bool SP2 = true>
; DI void gemm_phase(LAS unsigned char* lds, const Gemm g, const StaticOrder& S, const Epi& E) {
;     ...
;             PG8_LDA(At, 1, 1); PG8_STAGE(PG8_SB(1, 0), b3, voffB); PG8_STAGE(PG8_SB(1, 1), b3 + hstepB, voffB); PG8_STAGE(PG8_SA(1, 0), a3, voffA);
;             PG8_WAIT_V(8); PG8_WAIT_L(0); PG8_BAR; PG8_MMA(1, 0, At, B0); PG8_MMA(1, 1, At, B1); PG8_BAR; PG8_SCHED;
;     ...
;         if constexpr (ALIGN_EPI) { if (wr == 0) PG8_BAR; }
	s_add_i32 s62, s91, s68
	v_lshl_add_u64 v[150:151], v[150:151], 0, s[20:21]
	s_mov_b32 m0, s62
	ds_read_b128 v[186:189], v148 offset:49152
	ds_read_b128 v[192:195], v148 offset:50176
	ds_read_b128 v[196:199], v148 offset:51200
	ds_read_b128 v[200:203], v148 offset:52224
	ds_read_b128 v[204:207], v148 offset:53248
	ds_read_b128 v[208:211], v148 offset:54272
	ds_read_b128 v[212:215], v148 offset:55296
	ds_read_b128 v[216:219], v148 offset:56320
	global_load_lds_dwordx4 v[150:151], off
	s_add_i32 m0, s62, 0x2000
	s_add_u32 s60, s60, 0x20080
	v_lshl_add_u64 v[150:151], v[220:221], 0, s[20:21]
	s_addc_u32 s61, s61, 0
	s_add_i32 s62, s92, s68
	global_load_lds_dwordx4 v[150:151], off
	v_lshl_add_u64 v[150:151], s[60:61], 0, v[132:133]
	s_mov_b32 m0, s62
	s_nop 0
	global_load_lds_dwordx4 v[150:151], off
	v_lshl_add_u64 v[150:151], s[60:61], 0, v[134:135]
	s_add_i32 m0, s62, 0x2000
	s_nop 0
	global_load_lds_dwordx4 v[150:151], off
	v_lshl_add_u64 v[150:151], v[222:223], 0, s[20:21]
	s_mov_b32 m0, s74
	s_nop 0
	global_load_lds_dwordx4 v[150:151], off
	v_lshl_add_u64 v[150:151], v[226:227], 0, s[20:21]
	s_mov_b32 m0, s75
	s_nop 0
	global_load_lds_dwordx4 v[150:151], off
	s_waitcnt vmcnt(8)
	s_waitcnt lgkmcnt(0)
	s_barrier
	s_setprio 0
	s_waitcnt lgkmcnt(0)
	v_mfma_f32_16x16x32_bf16 v[60:63], v[154:157], v[186:189], v[60:63]
	v_mfma_f32_16x16x32_bf16 v[56:59], v[162:165], v[186:189], v[56:59]
	v_mfma_f32_16x16x32_bf16 v[52:55], v[154:157], v[196:199], v[52:55]
	v_mfma_f32_16x16x32_bf16 v[48:51], v[162:165], v[196:199], v[48:51]
	v_mfma_f32_16x16x32_bf16 v[36:39], v[154:157], v[204:207], v[36:39]
	v_mfma_f32_16x16x32_bf16 v[32:35], v[162:165], v[204:207], v[32:35]
	v_mfma_f32_16x16x32_bf16 v[20:23], v[154:157], v[212:215], v[20:23]
	v_mfma_f32_16x16x32_bf16 v[16:19], v[162:165], v[212:215], v[16:19]
	v_mfma_f32_16x16x32_bf16 v[60:63], v[158:161], v[192:195], v[60:63]
	v_mfma_f32_16x16x32_bf16 v[56:59], v[166:169], v[192:195], v[56:59]
	v_mfma_f32_16x16x32_bf16 v[52:55], v[158:161], v[200:203], v[52:55]
	v_mfma_f32_16x16x32_bf16 v[48:51], v[166:169], v[200:203], v[48:51]
	v_mfma_f32_16x16x32_bf16 v[36:39], v[158:161], v[208:211], v[36:39]
	v_mfma_f32_16x16x32_bf16 v[32:35], v[166:169], v[208:211], v[32:35]
	v_mfma_f32_16x16x32_bf16 v[20:23], v[158:161], v[216:219], v[20:23]
	v_mfma_f32_16x16x32_bf16 v[16:19], v[166:169], v[216:219], v[16:19]
	v_mfma_f32_16x16x32_bf16 v[44:47], v[170:173], v[186:189], v[44:47]
	v_mfma_f32_16x16x32_bf16 v[40:43], v[178:181], v[186:189], v[40:43]
	v_mfma_f32_16x16x32_bf16 v[28:31], v[170:173], v[196:199], v[28:31]
	v_mfma_f32_16x16x32_bf16 v[24:27], v[178:181], v[196:199], v[24:27]
	v_mfma_f32_16x16x32_bf16 v[12:15], v[170:173], v[204:207], v[12:15]
	v_mfma_f32_16x16x32_bf16 v[8:11], v[178:181], v[204:207], v[8:11]
	v_mfma_f32_16x16x32_bf16 v[4:7], v[170:173], v[212:215], v[4:7]
	v_mfma_f32_16x16x32_bf16 v[0:3], v[178:181], v[212:215], v[0:3]
	v_mfma_f32_16x16x32_bf16 v[44:47], v[174:177], v[192:195], v[44:47]
	v_mfma_f32_16x16x32_bf16 v[40:43], v[182:185], v[192:195], v[40:43]
	v_mfma_f32_16x16x32_bf16 v[28:31], v[174:177], v[200:203], v[28:31]
	v_mfma_f32_16x16x32_bf16 v[24:27], v[182:185], v[200:203], v[24:27]
	v_mfma_f32_16x16x32_bf16 v[12:15], v[174:177], v[208:211], v[12:15]
	v_mfma_f32_16x16x32_bf16 v[8:11], v[182:185], v[208:211], v[8:11]
	v_mfma_f32_16x16x32_bf16 v[4:7], v[174:177], v[216:219], v[4:7]
	v_mfma_f32_16x16x32_bf16 v[0:3], v[182:185], v[216:219], v[0:3]
	s_setprio 1
	s_barrier
	s_add_i32 s90, s90, 2
	s_add_u32 s0, s0, 0x100
	s_addc_u32 s1, s1, 0
	s_add_u32 s88, s88, 0x100
	s_addc_u32 s89, s89, 0
	s_cmp_gt_u32 s90, 5
	s_cbranch_scc0 .LBB0_360
	s_and_b64 vcc, exec, s[22:23]
	s_cbranch_vccz .LBB0_363
	s_barrier

; #define PG8_STAGE(bufoff, gbase, voff) do { _Pragma("unroll") for (int _i = 0; _i < 2; ++_i) \
;         __builtin_amdgcn_global_load_lds((const unsigned*)((const char*)(gbase) + (voff)[_i]), (LAS unsigned*)(lds + (bufoff) + ldsw + _i * 8192), 16, 0, 0); } while (0)
; #define PG8_LDA(dst, b, h) do { _Pragma("unroll") for (int m = 0; m < 4; ++m) _Pragma("unroll") for (int k = 0; k < 2; ++k) dst[m][k] = *(const LAS bf16x8*)(lds + PG8_SA(b, h) + aoff + m * 2048 + k * 1024); } while (0)
; #define PG8_LDB(dst, b, h) do { _Pragma("unroll") for (int n = 0; n < 2; ++n) _Pragma("unroll") for (int k = 0; k < 2; ++k) dst[n][k] = *(const LAS bf16x8*)(lds + PG8_SB(b, h) + boff + n * 2048 + k * 1024); } while (0)
; #define PG8_MMA(ai, bj, At, Bt) do { __builtin_amdgcn_s_setprio(1); _Pragma("unroll") for (int m = 0; m < 4; ++m) _Pragma("unroll") for (int n = 0; n < 2; ++n) _Pragma("unroll") for (int k = 0; k < 2; ++k) \
;         acc[ai][bj][m][n] = __builtin_amdgcn_mfma_f32_16x16x32_bf16(Bt[n][k], At[m][k], acc[ai][bj][m][n], 0, 0, 0); __builtin_amdgcn_s_setprio(0); } while (0)
; #define PG8_BAR __builtin_amdgcn_s_barrier()
; template <class Epi, bool ALIGN_EPI = true, bool SP2 = true>
; DI void gemm_phase(LAS unsigned char* lds, const Gemm g, const StaticOrder& S, const Epi& E) {
;     ...
;             const bool last = (t == nt - 2);
;             const char* a1 = cA + (size_t)(t + 1) * kstep;
;             const char* a2 = last ? nA : cA + (size_t)(t + 2) * kstep; const char* b2 = last ? nB : cB + (size_t)(t + 2) * kstep;
;             const char* a3 = a2 + kstep; const char* b3 = b2 + kstep;
;             if (Epi::MID) { if (t == (nt >> 1)) {
;                 if constexpr (ALIGN_EPI) { if (wr == 0) PG8_BAR; }
;                 E.mid(acc, cur, wr, wc, fr, fq);
;                 if constexpr (ALIGN_EPI) { if (wr == 1) PG8_BAR; } } }
;             if constexpr (SP2) {
;             PG8_LDB(B0, 0, 0); PG8_LDB(B1, 0, 1); PG8_SCHED; PG8_LDA(At, 0, 0); PG8_STAGE(PG8_SA(1, 1), a1 + hstepA, voffA);
;             PG8_WAIT_V(8); PG8_WAIT_L(0); PG8_BAR; PG8_MMA(0, 0, At, B0); PG8_MMA(0, 1, At, B1); PG8_BAR; PG8_SCHED;
;             PG8_LDA(At, 0, 1); PG8_STAGE(PG8_SB(0, 0), b2, voffB); PG8_STAGE(PG8_SB(0, 1), b2 + hstepB, voffB); PG8_STAGE(PG8_SA(0, 0), a2, voffA);
;             PG8_WAIT_V(8); PG8_WAIT_L(0); PG8_BAR; PG8_MMA(1, 0, At, B0); PG8_MMA(1, 1, At, B1); PG8_BAR; PG8_SCHED;
.LBB0_755:
	v_add_u32_e32 v1, s67, v227
	ds_read_b128 v[132:135], v1
	ds_read_b128 v[136:139], v1 offset:1024
	ds_read_b128 v[140:143], v1 offset:2048
	ds_read_b128 v[144:147], v1 offset:3072
	v_add_u32_e32 v1, s68, v227
	s_add_u32 s8, s26, s30
	ds_read_b128 v[148:151], v1
	ds_read_b128 v[152:155], v1 offset:1024
	ds_read_b128 v[156:159], v1 offset:2048
	ds_read_b128 v[160:163], v1 offset:3072
	s_addc_u32 s9, s27, s31
	s_add_u32 s8, s8, 0x100
	s_addc_u32 s9, s9, 0
	s_add_u32 s34, s73, s30
	s_addc_u32 s35, s74, s31
	s_cmpk_eq_i32 s30, 0x1f00
	s_cselect_b32 s37, s21, s9
	s_cselect_b32 s36, s69, s8
	s_cselect_b32 s35, s70, s35
	s_cselect_b32 s34, s71, s34
	v_lshl_add_u64 v[2:3], v[188:189], 0, s[30:31]
	s_add_i32 m0, s43, 0xc000
	ds_read_b128 v[164:167], v229
	ds_read_b128 v[168:171], v229 offset:1024
	ds_read_b128 v[172:175], v229 offset:2048
	ds_read_b128 v[176:179], v229 offset:3072
	ds_read_b128 v[180:183], v229 offset:4096
	ds_read_b128 v[184:187], v229 offset:5120
	ds_read_b128 v[212:215], v229 offset:6144
	ds_read_b128 v[216:219], v229 offset:7168
	global_load_lds_dwordx4 v[2:3], off
	v_lshl_add_u64 v[2:3], v[190:191], 0, s[30:31]
	s_add_i32 m0, s43, 0xe000
	s_nop 0
	global_load_lds_dwordx4 v[2:3], off
	s_waitcnt vmcnt(8)
	s_waitcnt lgkmcnt(0)
	s_barrier
	s_setprio 0
	s_waitcnt lgkmcnt(0)
	v_mfma_f32_16x16x32_bf16 v[128:131], v[132:135], v[164:167], v[128:131]
	v_mfma_f32_16x16x32_bf16 v[124:127], v[140:143], v[164:167], v[124:127]
	v_mfma_f32_16x16x32_bf16 v[112:115], v[132:135], v[172:175], v[112:115]
	v_mfma_f32_16x16x32_bf16 v[108:111], v[140:143], v[172:175], v[108:111]
	v_mfma_f32_16x16x32_bf16 v[96:99], v[132:135], v[180:183], v[96:99]
	v_mfma_f32_16x16x32_bf16 v[92:95], v[140:143], v[180:183], v[92:95]
	v_mfma_f32_16x16x32_bf16 v[80:83], v[132:135], v[212:215], v[80:83]
	v_mfma_f32_16x16x32_bf16 v[76:79], v[140:143], v[212:215], v[76:79]
	v_mfma_f32_16x16x32_bf16 v[128:131], v[136:139], v[168:171], v[128:131]
	v_mfma_f32_16x16x32_bf16 v[124:127], v[144:147], v[168:171], v[124:127]
	v_mfma_f32_16x16x32_bf16 v[112:115], v[136:139], v[176:179], v[112:115]
	v_mfma_f32_16x16x32_bf16 v[108:111], v[144:147], v[176:179], v[108:111]
	v_mfma_f32_16x16x32_bf16 v[96:99], v[136:139], v[184:187], v[96:99]
	v_mfma_f32_16x16x32_bf16 v[92:95], v[144:147], v[184:187], v[92:95]
	v_mfma_f32_16x16x32_bf16 v[80:83], v[136:139], v[216:219], v[80:83]
	v_mfma_f32_16x16x32_bf16 v[76:79], v[144:147], v[216:219], v[76:79]
	v_mfma_f32_16x16x32_bf16 v[120:123], v[148:151], v[164:167], v[120:123]
	v_mfma_f32_16x16x32_bf16 v[116:119], v[156:159], v[164:167], v[116:119]
	v_mfma_f32_16x16x32_bf16 v[104:107], v[148:151], v[172:175], v[104:107]
	v_mfma_f32_16x16x32_bf16 v[100:103], v[156:159], v[172:175], v[100:103]
	v_mfma_f32_16x16x32_bf16 v[88:91], v[148:151], v[180:183], v[88:91]
	v_mfma_f32_16x16x32_bf16 v[84:87], v[156:159], v[180:183], v[84:87]
	v_mfma_f32_16x16x32_bf16 v[72:75], v[148:151], v[212:215], v[72:75]
	v_mfma_f32_16x16x32_bf16 v[68:71], v[156:159], v[212:215], v[68:71]
	v_mfma_f32_16x16x32_bf16 v[120:123], v[152:155], v[168:171], v[120:123]
	v_mfma_f32_16x16x32_bf16 v[116:119], v[160:163], v[168:171], v[116:119]
	v_mfma_f32_16x16x32_bf16 v[104:107], v[152:155], v[176:179], v[104:107]
	v_mfma_f32_16x16x32_bf16 v[100:103], v[160:163], v[176:179], v[100:103]
	v_mfma_f32_16x16x32_bf16 v[88:91], v[152:155], v[184:187], v[88:91]
	v_mfma_f32_16x16x32_bf16 v[84:87], v[160:163], v[184:187], v[84:87]
	v_mfma_f32_16x16x32_bf16 v[72:75], v[152:155], v[216:219], v[72:75]
	v_mfma_f32_16x16x32_bf16 v[68:71], v[160:163], v[216:219], v[68:71]
	s_setprio 1
	s_barrier
	s_add_i32 s8, s67, s42
	v_lshl_add_u64 v[220:221], s[34:35], 0, v[194:195]
	s_mov_b32 m0, s8
	ds_read_b128 v[164:167], v229 offset:16384
	ds_read_b128 v[168:171], v229 offset:17408
	ds_read_b128 v[172:175], v229 offset:18432
	ds_read_b128 v[176:179], v229 offset:19456
	ds_read_b128 v[180:183], v229 offset:20480
	ds_read_b128 v[184:187], v229 offset:21504
	ds_read_b128 v[212:215], v229 offset:22528
	ds_read_b128 v[216:219], v229 offset:23552
	global_load_lds_dwordx4 v[220:221], off
	s_add_i32 m0, s8, 0x2000
	s_add_u32 s76, s34, 0x100000
	v_lshl_add_u64 v[222:223], s[34:35], 0, v[198:199]
	s_addc_u32 s77, s35, 0
	s_add_i32 s8, s68, s42
	global_load_lds_dwordx4 v[222:223], off
	v_lshl_add_u64 v[2:3], s[76:77], 0, v[194:195]
	s_mov_b32 m0, s8
	v_lshl_add_u64 v[232:233], s[36:37], 0, v[192:193]
	global_load_lds_dwordx4 v[2:3], off
	v_lshl_add_u64 v[2:3], s[76:77], 0, v[198:199]
	s_add_i32 m0, s8, 0x2000
	v_lshl_add_u64 v[234:235], s[36:37], 0, v[196:197]
	global_load_lds_dwordx4 v[2:3], off
	s_mov_b32 m0, s43
	s_nop 0
	global_load_lds_dwordx4 v[232:233], off
	s_mov_b32 m0, s44
	s_nop 0
	global_load_lds_dwordx4 v[234:235], off
	s_waitcnt vmcnt(8)
	s_waitcnt lgkmcnt(0)
	s_barrier
; #define PG8_STAGE(bufoff, gbase, voff) do { _Pragma("unroll") for (int _i = 0; _i < 2; ++_i) \
;         __builtin_amdgcn_global_load_lds((const unsigned*)((const char*)(gbase) + (voff)[_i]), (LAS unsigned*)(lds + (bufoff) + ldsw + _i * 8192), 16, 0, 0); } while (0)
; #define PG8_LDA(dst, b, h) do { _Pragma("unroll") for (int m = 0; m < 4; ++m) _Pragma("unroll") for (int k = 0; k < 2; ++k) dst[m][k] = *(const LAS bf16x8*)(lds + PG8_SA(b, h) + aoff + m * 2048 + k * 1024); } while (0)
; #define PG8_LDB(dst, b, h) do { _Pragma("unroll") for (int n = 0; n < 2; ++n) _Pragma("unroll") for (int k = 0; k < 2; ++k) dst[n][k] = *(const LAS bf16x8*)(lds + PG8_SB(b, h) + boff + n * 2048 + k * 1024); } while (0)
; #define PG8_MMA(ai, bj, At, Bt) do { __builtin_amdgcn_s_setprio(1); _Pragma("unroll") for (int m = 0; m < 4; ++m) _Pragma("unroll") for (int n = 0; n < 2; ++n) _Pragma("unroll") for (int k = 0; k < 2; ++k) \
;         acc[ai][bj][m][n] = __builtin_amdgcn_mfma_f32_16x16x32_bf16(Bt[n][k], At[m][k], acc[ai][bj][m][n], 0, 0, 0); __builtin_amdgcn_s_setprio(0); } while (0)
; #define PG8_WAIT_V(n) asm volatile("s_waitcnt vmcnt(" #n ")" ::: "memory")
; #define PG8_WAIT_L(n) asm volatile("s_waitcnt lgkmcnt(" #n ")" ::: "memory")
; #define PG8_BAR __builtin_amdgcn_s_barrier()
; #define PG8_SCHED __builtin_amdgcn_sched_barrier(0)
; template <class Epi, bool ALIGN_EPI = true, bool SP2 = true>
; DI void gemm_phase(LAS unsigned char* lds, const Gemm g, const StaticOrder& S, const Epi& E) {
;     ...
;             PG8_WAIT_V(8); PG8_WAIT_L(0); PG8_BAR; PG8_MMA(1, 0, At, B0); PG8_MMA(1, 1, At, B1); PG8_BAR; PG8_SCHED;
;             PG8_LDB(B0, 1, 0); PG8_LDB(B1, 1, 1); PG8_SCHED; PG8_LDA(At, 1, 0); PG8_STAGE(PG8_SA(0, 1), a2 + hstepA, voffA);
;             PG8_WAIT_V(8); PG8_WAIT_L(0); PG8_BAR; PG8_MMA(0, 0, At, B0); PG8_MMA(0, 1, At, B1); PG8_BAR; PG8_SCHED;
	s_setprio 0
	s_waitcnt lgkmcnt(0)
	v_mfma_f32_16x16x32_bf16 v[64:67], v[132:135], v[164:167], v[64:67]
	v_mfma_f32_16x16x32_bf16 v[60:63], v[140:143], v[164:167], v[60:63]
	v_mfma_f32_16x16x32_bf16 v[48:51], v[132:135], v[172:175], v[48:51]
	v_mfma_f32_16x16x32_bf16 v[44:47], v[140:143], v[172:175], v[44:47]
	v_mfma_f32_16x16x32_bf16 v[32:35], v[132:135], v[180:183], v[32:35]
	v_mfma_f32_16x16x32_bf16 v[28:31], v[140:143], v[180:183], v[28:31]
	v_mfma_f32_16x16x32_bf16 v[16:19], v[132:135], v[212:215], v[16:19]
	v_mfma_f32_16x16x32_bf16 v[12:15], v[140:143], v[212:215], v[12:15]
	v_mfma_f32_16x16x32_bf16 v[64:67], v[136:139], v[168:171], v[64:67]
	v_mfma_f32_16x16x32_bf16 v[60:63], v[144:147], v[168:171], v[60:63]
	v_mfma_f32_16x16x32_bf16 v[48:51], v[136:139], v[176:179], v[48:51]
	v_mfma_f32_16x16x32_bf16 v[44:47], v[144:147], v[176:179], v[44:47]
	v_mfma_f32_16x16x32_bf16 v[32:35], v[136:139], v[184:187], v[32:35]
	v_mfma_f32_16x16x32_bf16 v[28:31], v[144:147], v[184:187], v[28:31]
	v_mfma_f32_16x16x32_bf16 v[16:19], v[136:139], v[216:219], v[16:19]
	v_mfma_f32_16x16x32_bf16 v[12:15], v[144:147], v[216:219], v[12:15]
	v_mfma_f32_16x16x32_bf16 v[56:59], v[148:151], v[164:167], v[56:59]
	v_mfma_f32_16x16x32_bf16 v[52:55], v[156:159], v[164:167], v[52:55]
	v_mfma_f32_16x16x32_bf16 v[40:43], v[148:151], v[172:175], v[40:43]
	v_mfma_f32_16x16x32_bf16 v[36:39], v[156:159], v[172:175], v[36:39]
	v_mfma_f32_16x16x32_bf16 v[24:27], v[148:151], v[180:183], v[24:27]
	v_mfma_f32_16x16x32_bf16 v[20:23], v[156:159], v[180:183], v[20:23]
	v_mfma_f32_16x16x32_bf16 v[8:11], v[148:151], v[212:215], v[8:11]
	v_mfma_f32_16x16x32_bf16 v[2:5], v[156:159], v[212:215], v[4:7]
	v_mfma_f32_16x16x32_bf16 v[56:59], v[152:155], v[168:171], v[56:59]
	v_mfma_f32_16x16x32_bf16 v[52:55], v[160:163], v[168:171], v[52:55]
	v_mfma_f32_16x16x32_bf16 v[40:43], v[152:155], v[176:179], v[40:43]
	v_mfma_f32_16x16x32_bf16 v[36:39], v[160:163], v[176:179], v[36:39]
	v_mfma_f32_16x16x32_bf16 v[24:27], v[152:155], v[184:187], v[24:27]
	v_mfma_f32_16x16x32_bf16 v[20:23], v[160:163], v[184:187], v[20:23]
	v_mfma_f32_16x16x32_bf16 v[8:11], v[152:155], v[216:219], v[8:11]
	v_mfma_f32_16x16x32_bf16 v[2:5], v[160:163], v[216:219], v[2:5]
	s_setprio 1
	s_barrier
	s_add_i32 s8, 0, 0x18000
	v_add_u32_e32 v1, s8, v227
	s_add_i32 s9, 0, 0x1c000
	ds_read_b128 v[132:135], v1
	ds_read_b128 v[136:139], v1 offset:1024
	ds_read_b128 v[140:143], v1 offset:2048
	ds_read_b128 v[144:147], v1 offset:3072
	v_add_u32_e32 v1, s9, v227
	ds_read_b128 v[148:151], v1
	ds_read_b128 v[152:155], v1 offset:1024
	ds_read_b128 v[156:159], v1 offset:2048
	ds_read_b128 v[160:163], v1 offset:3072
	s_add_u32 s36, s36, 0x100000
	s_addc_u32 s37, s37, 0
	s_mov_b32 m0, s45
	v_lshl_add_u64 v[6:7], s[36:37], 0, v[192:193]
	ds_read_b128 v[164:167], v229 offset:32768
	ds_read_b128 v[168:171], v229 offset:33792
	ds_read_b128 v[172:175], v229 offset:34816
	ds_read_b128 v[176:179], v229 offset:35840
	ds_read_b128 v[180:183], v229 offset:36864
	ds_read_b128 v[184:187], v229 offset:37888
	ds_read_b128 v[212:215], v229 offset:38912
	ds_read_b128 v[216:219], v229 offset:39936
	global_load_lds_dwordx4 v[6:7], off
	v_lshl_add_u64 v[6:7], s[36:37], 0, v[196:197]
	s_mov_b32 m0, s46
	s_nop 0
	global_load_lds_dwordx4 v[6:7], off
	s_waitcnt vmcnt(8)
	s_waitcnt lgkmcnt(0)
	s_barrier
	s_setprio 0
	s_waitcnt lgkmcnt(0)
	v_mfma_f32_16x16x32_bf16 v[128:131], v[132:135], v[164:167], v[128:131]
	v_mfma_f32_16x16x32_bf16 v[124:127], v[140:143], v[164:167], v[124:127]
	v_mfma_f32_16x16x32_bf16 v[112:115], v[132:135], v[172:175], v[112:115]
	v_mfma_f32_16x16x32_bf16 v[108:111], v[140:143], v[172:175], v[108:111]
	v_mfma_f32_16x16x32_bf16 v[96:99], v[132:135], v[180:183], v[96:99]
	v_mfma_f32_16x16x32_bf16 v[92:95], v[140:143], v[180:183], v[92:95]
	v_mfma_f32_16x16x32_bf16 v[80:83], v[132:135], v[212:215], v[80:83]
	v_mfma_f32_16x16x32_bf16 v[76:79], v[140:143], v[212:215], v[76:79]
	v_mfma_f32_16x16x32_bf16 v[128:131], v[136:139], v[168:171], v[128:131]
	v_mfma_f32_16x16x32_bf16 v[124:127], v[144:147], v[168:171], v[124:127]
	v_mfma_f32_16x16x32_bf16 v[112:115], v[136:139], v[176:179], v[112:115]
	v_mfma_f32_16x16x32_bf16 v[108:111], v[144:147], v[176:179], v[108:111]
	v_mfma_f32_16x16x32_bf16 v[96:99], v[136:139], v[184:187], v[96:99]
	v_mfma_f32_16x16x32_bf16 v[92:95], v[144:147], v[184:187], v[92:95]
	v_mfma_f32_16x16x32_bf16 v[80:83], v[136:139], v[216:219], v[80:83]
	v_mfma_f32_16x16x32_bf16 v[76:79], v[144:147], v[216:219], v[76:79]
	v_mfma_f32_16x16x32_bf16 v[120:123], v[148:151], v[164:167], v[120:123]
	v_mfma_f32_16x16x32_bf16 v[116:119], v[156:159], v[164:167], v[116:119]
	v_mfma_f32_16x16x32_bf16 v[104:107], v[148:151], v[172:175], v[104:107]
	v_mfma_f32_16x16x32_bf16 v[100:103], v[156:159], v[172:175], v[100:103]
	v_mfma_f32_16x16x32_bf16 v[88:91], v[148:151], v[180:183], v[88:91]
	v_mfma_f32_16x16x32_bf16 v[84:87], v[156:159], v[180:183], v[84:87]
	v_mfma_f32_16x16x32_bf16 v[72:75], v[148:151], v[212:215], v[72:75]
	v_mfma_f32_16x16x32_bf16 v[68:71], v[156:159], v[212:215], v[68:71]
	v_mfma_f32_16x16x32_bf16 v[120:123], v[152:155], v[168:171], v[120:123]
	v_mfma_f32_16x16x32_bf16 v[116:119], v[160:163], v[168:171], v[116:119]
	v_mfma_f32_16x16x32_bf16 v[104:107], v[152:155], v[176:179], v[104:107]
	v_mfma_f32_16x16x32_bf16 v[100:103], v[160:163], v[176:179], v[100:103]
	v_mfma_f32_16x16x32_bf16 v[88:91], v[152:155], v[184:187], v[88:91]
	v_mfma_f32_16x16x32_bf16 v[84:87], v[160:163], v[184:187], v[84:87]
	v_mfma_f32_16x16x32_bf16 v[72:75], v[152:155], v[216:219], v[72:75]
	v_mfma_f32_16x16x32_bf16 v[68:71], v[160:163], v[216:219], v[68:71]
	s_setprio 1
	s_barrier
; #define PG8_STAGE(bufoff, gbase, voff) do { _Pragma("unroll") for (int _i = 0; _i < 2; ++_i) \
;         __builtin_amdgcn_global_load_lds((const unsigned*)((const char*)(gbase) + (voff)[_i]), (LAS unsigned*)(lds + (bufoff) + ldsw + _i * 8192), 16, 0, 0); } while (0)
; #define PG8_LDA(dst, b, h) do { _Pragma("unroll") for (int m = 0; m < 4; ++m) _Pragma("unroll") for (int k = 0; k < 2; ++k) dst[m][k] = *(const LAS bf16x8*)(lds + PG8_SA(b, h) + aoff + m * 2048 + k * 1024); } while (0)
; #define PG8_MMA(ai, bj, At, Bt) do { __builtin_amdgcn_s_setprio(1); _Pragma("unroll") for (int m = 0; m < 4; ++m) _Pragma("unroll") for (int n = 0; n < 2; ++n) _Pragma("unroll") for (int k = 0; k < 2; ++k) \
;         acc[ai][bj][m][n] = __builtin_amdgcn_mfma_f32_16x16x32_bf16(Bt[n][k], At[m][k], acc[ai][bj][m][n], 0, 0, 0); __builtin_amdgcn_s_setprio(0); } while (0)
; #define PG8_WAIT_V(n) asm volatile("s_waitcnt vmcnt(" #n ")" ::: "memory")
; #define PG8_WAIT_L(n) asm volatile("s_waitcnt lgkmcnt(" #n ")" ::: "memory")
; #define PG8_BAR __builtin_amdgcn_s_barrier()
; #define PG8_SCHED __builtin_amdgcn_sched_barrier(0)
; template <class Epi, bool ALIGN_EPI = true, bool SP2 = true>
; DI void gemm_phase(LAS unsigned char* lds, const Gemm g, const StaticOrder& S, const Epi& E) {
;     ...
;             PG8_LDA(At, 1, 1); PG8_STAGE(PG8_SB(1, 0), b3, voffB); PG8_STAGE(PG8_SB(1, 1), b3 + hstepB, voffB); PG8_STAGE(PG8_SA(1, 0), a3, voffA);
;             PG8_WAIT_V(8); PG8_WAIT_L(0); PG8_BAR; PG8_MMA(1, 0, At, B0); PG8_MMA(1, 1, At, B1); PG8_BAR; PG8_SCHED;
	s_add_i32 s8, s8, s42
	v_lshl_add_u64 v[6:7], v[220:221], 0, s[10:11]
	s_mov_b32 m0, s8
	ds_read_b128 v[164:167], v229 offset:49152
	ds_read_b128 v[168:171], v229 offset:50176
	ds_read_b128 v[172:175], v229 offset:51200
	ds_read_b128 v[176:179], v229 offset:52224
	ds_read_b128 v[180:183], v229 offset:53248
	ds_read_b128 v[184:187], v229 offset:54272
	ds_read_b128 v[212:215], v229 offset:55296
	ds_read_b128 v[216:219], v229 offset:56320
	global_load_lds_dwordx4 v[6:7], off
	s_add_i32 m0, s8, 0x2000
	s_add_u32 s34, s34, 0x100080
	v_lshl_add_u64 v[6:7], v[222:223], 0, s[10:11]
	s_addc_u32 s35, s35, 0
	s_add_i32 s8, s9, s42
	global_load_lds_dwordx4 v[6:7], off
	v_lshl_add_u64 v[6:7], s[34:35], 0, v[194:195]
	s_mov_b32 m0, s8
	s_nop 0
	global_load_lds_dwordx4 v[6:7], off
	v_lshl_add_u64 v[6:7], s[34:35], 0, v[198:199]
	s_add_i32 m0, s8, 0x2000
	s_nop 0
	global_load_lds_dwordx4 v[6:7], off
	v_lshl_add_u64 v[6:7], v[232:233], 0, s[10:11]
	s_mov_b32 m0, s51
	s_nop 0
	global_load_lds_dwordx4 v[6:7], off
	v_lshl_add_u64 v[6:7], v[234:235], 0, s[10:11]
	s_mov_b32 m0, s60
	s_nop 0
	global_load_lds_dwordx4 v[6:7], off
	s_waitcnt vmcnt(8)
	s_waitcnt lgkmcnt(0)
	s_barrier
	s_setprio 0
	s_waitcnt lgkmcnt(0)
	v_mfma_f32_16x16x32_bf16 v[64:67], v[132:135], v[164:167], v[64:67]
	v_mfma_f32_16x16x32_bf16 v[60:63], v[140:143], v[164:167], v[60:63]
	v_mfma_f32_16x16x32_bf16 v[48:51], v[132:135], v[172:175], v[48:51]
	v_mfma_f32_16x16x32_bf16 v[44:47], v[140:143], v[172:175], v[44:47]
	v_mfma_f32_16x16x32_bf16 v[32:35], v[132:135], v[180:183], v[32:35]
	v_mfma_f32_16x16x32_bf16 v[28:31], v[140:143], v[180:183], v[28:31]
	v_mfma_f32_16x16x32_bf16 v[16:19], v[132:135], v[212:215], v[16:19]
	v_mfma_f32_16x16x32_bf16 v[12:15], v[140:143], v[212:215], v[12:15]
	v_mfma_f32_16x16x32_bf16 v[64:67], v[136:139], v[168:171], v[64:67]
	v_mfma_f32_16x16x32_bf16 v[60:63], v[144:147], v[168:171], v[60:63]
	v_mfma_f32_16x16x32_bf16 v[48:51], v[136:139], v[176:179], v[48:51]
	v_mfma_f32_16x16x32_bf16 v[44:47], v[144:147], v[176:179], v[44:47]
	v_mfma_f32_16x16x32_bf16 v[32:35], v[136:139], v[184:187], v[32:35]
	v_mfma_f32_16x16x32_bf16 v[28:31], v[144:147], v[184:187], v[28:31]
	v_mfma_f32_16x16x32_bf16 v[16:19], v[136:139], v[216:219], v[16:19]
	v_mfma_f32_16x16x32_bf16 v[12:15], v[144:147], v[216:219], v[12:15]
	v_mfma_f32_16x16x32_bf16 v[56:59], v[148:151], v[164:167], v[56:59]
	v_mfma_f32_16x16x32_bf16 v[52:55], v[156:159], v[164:167], v[52:55]
	v_mfma_f32_16x16x32_bf16 v[40:43], v[148:151], v[172:175], v[40:43]
	v_mfma_f32_16x16x32_bf16 v[36:39], v[156:159], v[172:175], v[36:39]
	v_mfma_f32_16x16x32_bf16 v[24:27], v[148:151], v[180:183], v[24:27]
	v_mfma_f32_16x16x32_bf16 v[20:23], v[156:159], v[180:183], v[20:23]
	v_mfma_f32_16x16x32_bf16 v[6:9], v[148:151], v[212:215], v[8:11]
	v_mfma_f32_16x16x32_bf16 v[2:5], v[156:159], v[212:215], v[2:5]
	v_mfma_f32_16x16x32_bf16 v[56:59], v[152:155], v[168:171], v[56:59]
	v_mfma_f32_16x16x32_bf16 v[52:55], v[160:163], v[168:171], v[52:55]
	v_mfma_f32_16x16x32_bf16 v[40:43], v[152:155], v[176:179], v[40:43]
	v_mfma_f32_16x16x32_bf16 v[36:39], v[160:163], v[176:179], v[36:39]
	v_mfma_f32_16x16x32_bf16 v[24:27], v[152:155], v[184:187], v[24:27]
	v_mfma_f32_16x16x32_bf16 v[20:23], v[160:163], v[184:187], v[20:23]
	v_mfma_f32_16x16x32_bf16 v[8:11], v[152:155], v[216:219], v[6:9]
	v_mfma_f32_16x16x32_bf16 v[4:7], v[160:163], v[216:219], v[2:5]
	s_setprio 1
	s_barrier
	s_add_i32 s75, s75, 2
	s_add_u32 s30, s30, 0x100
	s_addc_u32 s31, s31, 0
	s_cmp_gt_u32 s75, 61
	s_cbranch_scc1 .LBB0_761

; #define PG8_STAGE(bufoff, gbase, voff) do { _Pragma("unroll") for (int _i = 0; _i < 2; ++_i) \
;         __builtin_amdgcn_global_load_lds((const unsigned*)((const char*)(gbase) + (voff)[_i]), (LAS unsigned*)(lds + (bufoff) + ldsw + _i * 8192), 16, 0, 0); } while (0)
; #define PG8_LDA(dst, b, h) do { _Pragma("unroll") for (int m = 0; m < 4; ++m) _Pragma("unroll") for (int k = 0; k < 2; ++k) dst[m][k] = *(const LAS bf16x8*)(lds + PG8_SA(b, h) + aoff + m * 2048 + k * 1024); } while (0)
; #define PG8_LDB(dst, b, h) do { _Pragma("unroll") for (int n = 0; n < 2; ++n) _Pragma("unroll") for (int k = 0; k < 2; ++k) dst[n][k] = *(const LAS bf16x8*)(lds + PG8_SB(b, h) + boff + n * 2048 + k * 1024); } while (0)
; #define PG8_MMA(ai, bj, At, Bt) do { __builtin_amdgcn_s_setprio(1); _Pragma("unroll") for (int m = 0; m < 4; ++m) _Pragma("unroll") for (int n = 0; n < 2; ++n) _Pragma("unroll") for (int k = 0; k < 2; ++k) \
;         acc[ai][bj][m][n] = __builtin_amdgcn_mfma_f32_16x16x32_bf16(Bt[n][k], At[m][k], acc[ai][bj][m][n], 0, 0, 0); __builtin_amdgcn_s_setprio(0); } while (0)
; #define PG8_BAR __builtin_amdgcn_s_barrier()
; template <class Epi, bool ALIGN_EPI = true, bool SP2 = true>
; DI void gemm_phase(LAS unsigned char* lds, const Gemm g, const StaticOrder& S, const Epi& E) {
;     ...
;             const bool last = (t == nt - 2);
;             const char* a1 = cA + (size_t)(t + 1) * kstep;
;             const char* a2 = last ? nA : cA + (size_t)(t + 2) * kstep; const char* b2 = last ? nB : cB + (size_t)(t + 2) * kstep;
;             const char* a3 = a2 + kstep; const char* b3 = b2 + kstep;
;             if (Epi::MID) { if (t == (nt >> 1)) {
;                 if constexpr (ALIGN_EPI) { if (wr == 0) PG8_BAR; }
;                 E.mid(acc, cur, wr, wc, fr, fq);
;                 if constexpr (ALIGN_EPI) { if (wr == 1) PG8_BAR; } } }
;             if constexpr (SP2) {
;             PG8_LDB(B0, 0, 0); PG8_LDB(B1, 0, 1); PG8_SCHED; PG8_LDA(At, 0, 0); PG8_STAGE(PG8_SA(1, 1), a1 + hstepA, voffA);
;             PG8_WAIT_V(8); PG8_WAIT_L(0); PG8_BAR; PG8_MMA(0, 0, At, B0); PG8_MMA(0, 1, At, B1); PG8_BAR; PG8_SCHED;
;             PG8_LDA(At, 0, 1); PG8_STAGE(PG8_SB(0, 0), b2, voffB); PG8_STAGE(PG8_SB(0, 1), b2 + hstepB, voffB); PG8_STAGE(PG8_SA(0, 0), a2, voffA);
;             PG8_WAIT_V(8); PG8_WAIT_L(0); PG8_BAR; PG8_MMA(1, 0, At, B0); PG8_MMA(1, 1, At, B1); PG8_BAR; PG8_SCHED;
.LBB0_839:
	ds_read_b128 v[140:143], v149
	ds_read_b128 v[152:155], v149 offset:1024
	ds_read_b128 v[156:159], v149 offset:2048
	ds_read_b128 v[160:163], v149 offset:3072
	ds_read_b128 v[164:167], v150
	ds_read_b128 v[168:171], v150 offset:1024
	ds_read_b128 v[172:175], v150 offset:2048
	ds_read_b128 v[176:179], v150 offset:3072
	s_add_u32 s34, s30, 0xfff00080
	s_addc_u32 s35, s31, -1
	s_cmp_eq_u32 s59, 60
	s_cselect_b32 s37, s23, s35
	s_cselect_b32 s36, s50, s34
	s_cselect_b32 s35, s21, s57
	s_cselect_b32 s34, s51, s56
	v_lshl_add_u64 v[144:145], s[30:31], 0, v[132:133]
	s_add_i32 m0, s29, 0xc000
	ds_read_b128 v[180:183], v151
	ds_read_b128 v[184:187], v151 offset:1024
	ds_read_b128 v[188:191], v151 offset:2048
	ds_read_b128 v[192:195], v151 offset:3072
	ds_read_b128 v[196:199], v151 offset:4096
	ds_read_b128 v[200:203], v151 offset:5120
	ds_read_b128 v[204:207], v151 offset:6144
	ds_read_b128 v[208:211], v151 offset:7168
	global_load_lds_dwordx4 v[144:145], off
	v_lshl_add_u64 v[144:145], s[30:31], 0, v[134:135]
	s_add_i32 m0, s29, 0xe000
	s_nop 0
	global_load_lds_dwordx4 v[144:145], off
	s_waitcnt vmcnt(8)
	s_waitcnt lgkmcnt(0)
	s_barrier
	s_setprio 0
	s_waitcnt lgkmcnt(0)
	v_mfma_f32_16x16x32_bf16 v[124:127], v[140:143], v[180:183], v[124:127]
	v_mfma_f32_16x16x32_bf16 v[120:123], v[156:159], v[180:183], v[120:123]
	v_mfma_f32_16x16x32_bf16 v[116:119], v[140:143], v[188:191], v[116:119]
	v_mfma_f32_16x16x32_bf16 v[112:115], v[156:159], v[188:191], v[112:115]
	v_mfma_f32_16x16x32_bf16 v[108:111], v[140:143], v[196:199], v[108:111]
	v_mfma_f32_16x16x32_bf16 v[100:103], v[156:159], v[196:199], v[100:103]
	v_mfma_f32_16x16x32_bf16 v[92:95], v[140:143], v[204:207], v[92:95]
	v_mfma_f32_16x16x32_bf16 v[80:83], v[156:159], v[204:207], v[80:83]
	v_mfma_f32_16x16x32_bf16 v[124:127], v[152:155], v[184:187], v[124:127]
	v_mfma_f32_16x16x32_bf16 v[120:123], v[160:163], v[184:187], v[120:123]
	v_mfma_f32_16x16x32_bf16 v[116:119], v[152:155], v[192:195], v[116:119]
	v_mfma_f32_16x16x32_bf16 v[112:115], v[160:163], v[192:195], v[112:115]
	v_mfma_f32_16x16x32_bf16 v[108:111], v[152:155], v[200:203], v[108:111]
	v_mfma_f32_16x16x32_bf16 v[100:103], v[160:163], v[200:203], v[100:103]
	v_mfma_f32_16x16x32_bf16 v[92:95], v[152:155], v[208:211], v[92:95]
	v_mfma_f32_16x16x32_bf16 v[80:83], v[160:163], v[208:211], v[80:83]
	v_mfma_f32_16x16x32_bf16 v[104:107], v[164:167], v[180:183], v[104:107]
	v_mfma_f32_16x16x32_bf16 v[96:99], v[172:175], v[180:183], v[96:99]
	v_mfma_f32_16x16x32_bf16 v[88:91], v[164:167], v[188:191], v[88:91]
	v_mfma_f32_16x16x32_bf16 v[84:87], v[172:175], v[188:191], v[84:87]
	v_mfma_f32_16x16x32_bf16 v[76:79], v[164:167], v[196:199], v[76:79]
	v_mfma_f32_16x16x32_bf16 v[72:75], v[172:175], v[196:199], v[72:75]
	v_mfma_f32_16x16x32_bf16 v[68:71], v[164:167], v[204:207], v[68:71]
	v_mfma_f32_16x16x32_bf16 v[64:67], v[172:175], v[204:207], v[64:67]
	v_mfma_f32_16x16x32_bf16 v[104:107], v[168:171], v[184:187], v[104:107]
	v_mfma_f32_16x16x32_bf16 v[96:99], v[176:179], v[184:187], v[96:99]
	v_mfma_f32_16x16x32_bf16 v[88:91], v[168:171], v[192:195], v[88:91]
	v_mfma_f32_16x16x32_bf16 v[84:87], v[176:179], v[192:195], v[84:87]
	v_mfma_f32_16x16x32_bf16 v[76:79], v[168:171], v[200:203], v[76:79]
	v_mfma_f32_16x16x32_bf16 v[72:75], v[176:179], v[200:203], v[72:75]
	v_mfma_f32_16x16x32_bf16 v[68:71], v[168:171], v[208:211], v[68:71]
	v_mfma_f32_16x16x32_bf16 v[64:67], v[176:179], v[208:211], v[64:67]
	s_setprio 1
	s_barrier
	s_add_i32 s60, s47, s39
	v_lshl_add_u64 v[144:145], s[34:35], 0, v[128:129]
	s_mov_b32 m0, s60
	ds_read_b128 v[180:183], v151 offset:16384
	ds_read_b128 v[184:187], v151 offset:17408
	ds_read_b128 v[188:191], v151 offset:18432
	ds_read_b128 v[192:195], v151 offset:19456
	ds_read_b128 v[196:199], v151 offset:20480
	ds_read_b128 v[200:203], v151 offset:21504
	ds_read_b128 v[204:207], v151 offset:22528
	ds_read_b128 v[208:211], v151 offset:23552
	global_load_lds_dwordx4 v[144:145], off
	s_add_i32 m0, s60, 0x2000
	s_add_u32 s60, s34, 0x100000
	v_lshl_add_u64 v[212:213], s[34:35], 0, v[130:131]
	s_addc_u32 s61, s35, 0
	s_add_i32 s62, s48, s39
	global_load_lds_dwordx4 v[212:213], off
	v_lshl_add_u64 v[214:215], s[60:61], 0, v[128:129]
	s_mov_b32 m0, s62
	v_lshl_add_u64 v[216:217], s[36:37], 0, v[130:131]
	global_load_lds_dwordx4 v[214:215], off
	v_lshl_add_u64 v[214:215], s[60:61], 0, v[130:131]
	s_add_i32 m0, s62, 0x2000
	s_nop 0
	global_load_lds_dwordx4 v[214:215], off
	v_lshl_add_u64 v[214:215], s[36:37], 0, v[128:129]
	s_mov_b32 m0, s29
	s_nop 0
	global_load_lds_dwordx4 v[214:215], off
	s_mov_b32 m0, s40
	s_nop 0
	global_load_lds_dwordx4 v[216:217], off
	s_waitcnt vmcnt(8)
	s_waitcnt lgkmcnt(0)
	s_barrier
; #define PG8_STAGE(bufoff, gbase, voff) do { _Pragma("unroll") for (int _i = 0; _i < 2; ++_i) \
;         __builtin_amdgcn_global_load_lds((const unsigned*)((const char*)(gbase) + (voff)[_i]), (LAS unsigned*)(lds + (bufoff) + ldsw + _i * 8192), 16, 0, 0); } while (0)
; #define PG8_LDA(dst, b, h) do { _Pragma("unroll") for (int m = 0; m < 4; ++m) _Pragma("unroll") for (int k = 0; k < 2; ++k) dst[m][k] = *(const LAS bf16x8*)(lds + PG8_SA(b, h) + aoff + m * 2048 + k * 1024); } while (0)
; #define PG8_LDB(dst, b, h) do { _Pragma("unroll") for (int n = 0; n < 2; ++n) _Pragma("unroll") for (int k = 0; k < 2; ++k) dst[n][k] = *(const LAS bf16x8*)(lds + PG8_SB(b, h) + boff + n * 2048 + k * 1024); } while (0)
; #define PG8_MMA(ai, bj, At, Bt) do { __builtin_amdgcn_s_setprio(1); _Pragma("unroll") for (int m = 0; m < 4; ++m) _Pragma("unroll") for (int n = 0; n < 2; ++n) _Pragma("unroll") for (int k = 0; k < 2; ++k) \
;         acc[ai][bj][m][n] = __builtin_amdgcn_mfma_f32_16x16x32_bf16(Bt[n][k], At[m][k], acc[ai][bj][m][n], 0, 0, 0); __builtin_amdgcn_s_setprio(0); } while (0)
; #define PG8_WAIT_V(n) asm volatile("s_waitcnt vmcnt(" #n ")" ::: "memory")
; #define PG8_WAIT_L(n) asm volatile("s_waitcnt lgkmcnt(" #n ")" ::: "memory")
; #define PG8_BAR __builtin_amdgcn_s_barrier()
; #define PG8_SCHED __builtin_amdgcn_sched_barrier(0)
; template <class Epi, bool ALIGN_EPI = true, bool SP2 = true>
; DI void gemm_phase(LAS unsigned char* lds, const Gemm g, const StaticOrder& S, const Epi& E) {
;     ...
;             PG8_WAIT_V(8); PG8_WAIT_L(0); PG8_BAR; PG8_MMA(1, 0, At, B0); PG8_MMA(1, 1, At, B1); PG8_BAR; PG8_SCHED;
;             PG8_LDB(B0, 1, 0); PG8_LDB(B1, 1, 1); PG8_SCHED; PG8_LDA(At, 1, 0); PG8_STAGE(PG8_SA(0, 1), a2 + hstepA, voffA);
;             PG8_WAIT_V(8); PG8_WAIT_L(0); PG8_BAR; PG8_MMA(0, 0, At, B0); PG8_MMA(0, 1, At, B1); PG8_BAR; PG8_SCHED;
	s_setprio 0
	s_waitcnt lgkmcnt(0)
	v_mfma_f32_16x16x32_bf16 v[60:63], v[140:143], v[180:183], v[60:63]
	v_mfma_f32_16x16x32_bf16 v[56:59], v[156:159], v[180:183], v[56:59]
	v_mfma_f32_16x16x32_bf16 v[52:55], v[140:143], v[188:191], v[52:55]
	v_mfma_f32_16x16x32_bf16 v[48:51], v[156:159], v[188:191], v[48:51]
	v_mfma_f32_16x16x32_bf16 v[44:47], v[140:143], v[196:199], v[44:47]
	v_mfma_f32_16x16x32_bf16 v[36:39], v[156:159], v[196:199], v[36:39]
	v_mfma_f32_16x16x32_bf16 v[28:31], v[140:143], v[204:207], v[28:31]
	v_mfma_f32_16x16x32_bf16 v[16:19], v[156:159], v[204:207], v[16:19]
	v_mfma_f32_16x16x32_bf16 v[60:63], v[152:155], v[184:187], v[60:63]
	v_mfma_f32_16x16x32_bf16 v[56:59], v[160:163], v[184:187], v[56:59]
	v_mfma_f32_16x16x32_bf16 v[52:55], v[152:155], v[192:195], v[52:55]
	v_mfma_f32_16x16x32_bf16 v[48:51], v[160:163], v[192:195], v[48:51]
	v_mfma_f32_16x16x32_bf16 v[44:47], v[152:155], v[200:203], v[44:47]
	v_mfma_f32_16x16x32_bf16 v[36:39], v[160:163], v[200:203], v[36:39]
	v_mfma_f32_16x16x32_bf16 v[28:31], v[152:155], v[208:211], v[28:31]
	v_mfma_f32_16x16x32_bf16 v[16:19], v[160:163], v[208:211], v[16:19]
	v_mfma_f32_16x16x32_bf16 v[40:43], v[164:167], v[180:183], v[40:43]
	v_mfma_f32_16x16x32_bf16 v[32:35], v[172:175], v[180:183], v[32:35]
	v_mfma_f32_16x16x32_bf16 v[24:27], v[164:167], v[188:191], v[24:27]
	v_mfma_f32_16x16x32_bf16 v[20:23], v[172:175], v[188:191], v[20:23]
	v_mfma_f32_16x16x32_bf16 v[12:15], v[164:167], v[196:199], v[12:15]
	v_mfma_f32_16x16x32_bf16 v[8:11], v[172:175], v[196:199], v[8:11]
	v_mfma_f32_16x16x32_bf16 v[4:7], v[164:167], v[204:207], v[4:7]
	v_mfma_f32_16x16x32_bf16 v[0:3], v[172:175], v[204:207], v[0:3]
	v_mfma_f32_16x16x32_bf16 v[40:43], v[168:171], v[184:187], v[40:43]
	v_mfma_f32_16x16x32_bf16 v[32:35], v[176:179], v[184:187], v[32:35]
	v_mfma_f32_16x16x32_bf16 v[24:27], v[168:171], v[192:195], v[24:27]
	v_mfma_f32_16x16x32_bf16 v[20:23], v[176:179], v[192:195], v[20:23]
	v_mfma_f32_16x16x32_bf16 v[12:15], v[168:171], v[200:203], v[12:15]
	v_mfma_f32_16x16x32_bf16 v[8:11], v[176:179], v[200:203], v[8:11]
	v_mfma_f32_16x16x32_bf16 v[4:7], v[168:171], v[208:211], v[4:7]
	v_mfma_f32_16x16x32_bf16 v[0:3], v[176:179], v[208:211], v[0:3]
	s_setprio 1
	s_barrier
	s_add_i32 s60, 0, 0x18000
	s_add_i32 s61, 0, 0x1c000
	v_add_u32_e32 v160, s60, v147
	v_add_u32_e32 v176, s61, v147
	ds_read_b128 v[140:143], v160
	ds_read_b128 v[152:155], v160 offset:1024
	ds_read_b128 v[156:159], v160 offset:2048
	ds_read_b128 v[160:163], v160 offset:3072
	ds_read_b128 v[164:167], v176
	ds_read_b128 v[168:171], v176 offset:1024
	ds_read_b128 v[172:175], v176 offset:2048
	ds_read_b128 v[176:179], v176 offset:3072
	s_add_u32 s36, s36, 0x100000
	s_addc_u32 s37, s37, 0
	s_mov_b32 m0, s41
	v_lshl_add_u64 v[218:219], s[36:37], 0, v[128:129]
	ds_read_b128 v[180:183], v151 offset:32768
	ds_read_b128 v[184:187], v151 offset:33792
	ds_read_b128 v[188:191], v151 offset:34816
	ds_read_b128 v[192:195], v151 offset:35840
	ds_read_b128 v[196:199], v151 offset:36864
	ds_read_b128 v[200:203], v151 offset:37888
	ds_read_b128 v[204:207], v151 offset:38912
	ds_read_b128 v[208:211], v151 offset:39936
	global_load_lds_dwordx4 v[218:219], off
	v_lshl_add_u64 v[218:219], s[36:37], 0, v[130:131]
	s_mov_b32 m0, s42
	s_nop 0
	global_load_lds_dwordx4 v[218:219], off
	s_waitcnt vmcnt(8)
	s_waitcnt lgkmcnt(0)
	s_barrier
	s_setprio 0
	s_waitcnt lgkmcnt(0)
	v_mfma_f32_16x16x32_bf16 v[124:127], v[140:143], v[180:183], v[124:127]
	v_mfma_f32_16x16x32_bf16 v[120:123], v[156:159], v[180:183], v[120:123]
	v_mfma_f32_16x16x32_bf16 v[116:119], v[140:143], v[188:191], v[116:119]
	v_mfma_f32_16x16x32_bf16 v[112:115], v[156:159], v[188:191], v[112:115]
	v_mfma_f32_16x16x32_bf16 v[108:111], v[140:143], v[196:199], v[108:111]
	v_mfma_f32_16x16x32_bf16 v[100:103], v[156:159], v[196:199], v[100:103]
	v_mfma_f32_16x16x32_bf16 v[92:95], v[140:143], v[204:207], v[92:95]
	v_mfma_f32_16x16x32_bf16 v[80:83], v[156:159], v[204:207], v[80:83]
	v_mfma_f32_16x16x32_bf16 v[124:127], v[152:155], v[184:187], v[124:127]
	v_mfma_f32_16x16x32_bf16 v[120:123], v[160:163], v[184:187], v[120:123]
	v_mfma_f32_16x16x32_bf16 v[116:119], v[152:155], v[192:195], v[116:119]
	v_mfma_f32_16x16x32_bf16 v[112:115], v[160:163], v[192:195], v[112:115]
	v_mfma_f32_16x16x32_bf16 v[108:111], v[152:155], v[200:203], v[108:111]
	v_mfma_f32_16x16x32_bf16 v[100:103], v[160:163], v[200:203], v[100:103]
	v_mfma_f32_16x16x32_bf16 v[92:95], v[152:155], v[208:211], v[92:95]
	v_mfma_f32_16x16x32_bf16 v[80:83], v[160:163], v[208:211], v[80:83]
	v_mfma_f32_16x16x32_bf16 v[104:107], v[164:167], v[180:183], v[104:107]
	v_mfma_f32_16x16x32_bf16 v[96:99], v[172:175], v[180:183], v[96:99]
	v_mfma_f32_16x16x32_bf16 v[88:91], v[164:167], v[188:191], v[88:91]
	v_mfma_f32_16x16x32_bf16 v[84:87], v[172:175], v[188:191], v[84:87]
	v_mfma_f32_16x16x32_bf16 v[76:79], v[164:167], v[196:199], v[76:79]
	v_mfma_f32_16x16x32_bf16 v[72:75], v[172:175], v[196:199], v[72:75]
	v_mfma_f32_16x16x32_bf16 v[68:71], v[164:167], v[204:207], v[68:71]
	v_mfma_f32_16x16x32_bf16 v[64:67], v[172:175], v[204:207], v[64:67]
	v_mfma_f32_16x16x32_bf16 v[104:107], v[168:171], v[184:187], v[104:107]
	v_mfma_f32_16x16x32_bf16 v[96:99], v[176:179], v[184:187], v[96:99]
	v_mfma_f32_16x16x32_bf16 v[88:91], v[168:171], v[192:195], v[88:91]
	v_mfma_f32_16x16x32_bf16 v[84:87], v[176:179], v[192:195], v[84:87]
	v_mfma_f32_16x16x32_bf16 v[76:79], v[168:171], v[200:203], v[76:79]
	v_mfma_f32_16x16x32_bf16 v[72:75], v[176:179], v[200:203], v[72:75]
	v_mfma_f32_16x16x32_bf16 v[68:71], v[168:171], v[208:211], v[68:71]
	v_mfma_f32_16x16x32_bf16 v[64:67], v[176:179], v[208:211], v[64:67]
	s_setprio 1
	s_barrier
; #define PG8_STAGE(bufoff, gbase, voff) do { _Pragma("unroll") for (int _i = 0; _i < 2; ++_i) \
;         __builtin_amdgcn_global_load_lds((const unsigned*)((const char*)(gbase) + (voff)[_i]), (LAS unsigned*)(lds + (bufoff) + ldsw + _i * 8192), 16, 0, 0); } while (0)
; #define PG8_LDA(dst, b, h) do { _Pragma("unroll") for (int m = 0; m < 4; ++m) _Pragma("unroll") for (int k = 0; k < 2; ++k) dst[m][k] = *(const LAS bf16x8*)(lds + PG8_SA(b, h) + aoff + m * 2048 + k * 1024); } while (0)
; #define PG8_MMA(ai, bj, At, Bt) do { __builtin_amdgcn_s_setprio(1); _Pragma("unroll") for (int m = 0; m < 4; ++m) _Pragma("unroll") for (int n = 0; n < 2; ++n) _Pragma("unroll") for (int k = 0; k < 2; ++k) \
;         acc[ai][bj][m][n] = __builtin_amdgcn_mfma_f32_16x16x32_bf16(Bt[n][k], At[m][k], acc[ai][bj][m][n], 0, 0, 0); __builtin_amdgcn_s_setprio(0); } while (0)
; #define PG8_WAIT_V(n) asm volatile("s_waitcnt vmcnt(" #n ")" ::: "memory")
; #define PG8_WAIT_L(n) asm volatile("s_waitcnt lgkmcnt(" #n ")" ::: "memory")
; #define PG8_BAR __builtin_amdgcn_s_barrier()
; #define PG8_SCHED __builtin_amdgcn_sched_barrier(0)
; template <class Epi, bool ALIGN_EPI = true, bool SP2 = true>
; DI void gemm_phase(LAS unsigned char* lds, const Gemm g, const StaticOrder& S, const Epi& E) {
;     ...
;             PG8_LDA(At, 1, 1); PG8_STAGE(PG8_SB(1, 0), b3, voffB); PG8_STAGE(PG8_SB(1, 1), b3 + hstepB, voffB); PG8_STAGE(PG8_SA(1, 0), a3, voffA);
;             PG8_WAIT_V(8); PG8_WAIT_L(0); PG8_BAR; PG8_MMA(1, 0, At, B0); PG8_MMA(1, 1, At, B1); PG8_BAR; PG8_SCHED;
;     ...
;         if constexpr (ALIGN_EPI) { if (wr == 0) PG8_BAR; }
	s_add_i32 s36, s60, s39
	v_lshl_add_u64 v[144:145], v[144:145], 0, s[6:7]
	s_mov_b32 m0, s36
	ds_read_b128 v[180:183], v151 offset:49152
	ds_read_b128 v[184:187], v151 offset:50176
	ds_read_b128 v[188:191], v151 offset:51200
	ds_read_b128 v[192:195], v151 offset:52224
	ds_read_b128 v[196:199], v151 offset:53248
	ds_read_b128 v[200:203], v151 offset:54272
	ds_read_b128 v[204:207], v151 offset:55296
	ds_read_b128 v[208:211], v151 offset:56320
	global_load_lds_dwordx4 v[144:145], off
	s_add_i32 m0, s36, 0x2000
	s_add_u32 s34, s34, 0x100080
	v_lshl_add_u64 v[144:145], v[212:213], 0, s[6:7]
	s_addc_u32 s35, s35, 0
	s_add_i32 s36, s61, s39
	global_load_lds_dwordx4 v[144:145], off
	v_lshl_add_u64 v[144:145], s[34:35], 0, v[128:129]
	s_mov_b32 m0, s36
	s_nop 0
	global_load_lds_dwordx4 v[144:145], off
	v_lshl_add_u64 v[144:145], s[34:35], 0, v[130:131]
	s_add_i32 m0, s36, 0x2000
	s_nop 0
	global_load_lds_dwordx4 v[144:145], off
	v_lshl_add_u64 v[144:145], v[214:215], 0, s[6:7]
	s_mov_b32 m0, s44
	s_nop 0
	global_load_lds_dwordx4 v[144:145], off
	v_lshl_add_u64 v[144:145], v[216:217], 0, s[6:7]
	s_mov_b32 m0, s45
	s_nop 0
	global_load_lds_dwordx4 v[144:145], off
	s_waitcnt vmcnt(8)
	s_waitcnt lgkmcnt(0)
	s_barrier
	s_setprio 0
	s_waitcnt lgkmcnt(0)
	v_mfma_f32_16x16x32_bf16 v[60:63], v[140:143], v[180:183], v[60:63]
	v_mfma_f32_16x16x32_bf16 v[56:59], v[156:159], v[180:183], v[56:59]
	v_mfma_f32_16x16x32_bf16 v[52:55], v[140:143], v[188:191], v[52:55]
	v_mfma_f32_16x16x32_bf16 v[48:51], v[156:159], v[188:191], v[48:51]
	v_mfma_f32_16x16x32_bf16 v[44:47], v[140:143], v[196:199], v[44:47]
	v_mfma_f32_16x16x32_bf16 v[36:39], v[156:159], v[196:199], v[36:39]
	v_mfma_f32_16x16x32_bf16 v[28:31], v[140:143], v[204:207], v[28:31]
	v_mfma_f32_16x16x32_bf16 v[16:19], v[156:159], v[204:207], v[16:19]
	v_mfma_f32_16x16x32_bf16 v[60:63], v[152:155], v[184:187], v[60:63]
	v_mfma_f32_16x16x32_bf16 v[56:59], v[160:163], v[184:187], v[56:59]
	v_mfma_f32_16x16x32_bf16 v[52:55], v[152:155], v[192:195], v[52:55]
	v_mfma_f32_16x16x32_bf16 v[48:51], v[160:163], v[192:195], v[48:51]
	v_mfma_f32_16x16x32_bf16 v[44:47], v[152:155], v[200:203], v[44:47]
	v_mfma_f32_16x16x32_bf16 v[36:39], v[160:163], v[200:203], v[36:39]
	v_mfma_f32_16x16x32_bf16 v[28:31], v[152:155], v[208:211], v[28:31]
	v_mfma_f32_16x16x32_bf16 v[16:19], v[160:163], v[208:211], v[16:19]
	v_mfma_f32_16x16x32_bf16 v[40:43], v[164:167], v[180:183], v[40:43]
	v_mfma_f32_16x16x32_bf16 v[32:35], v[172:175], v[180:183], v[32:35]
	v_mfma_f32_16x16x32_bf16 v[24:27], v[164:167], v[188:191], v[24:27]
	v_mfma_f32_16x16x32_bf16 v[20:23], v[172:175], v[188:191], v[20:23]
	v_mfma_f32_16x16x32_bf16 v[12:15], v[164:167], v[196:199], v[12:15]
	v_mfma_f32_16x16x32_bf16 v[8:11], v[172:175], v[196:199], v[8:11]
	v_mfma_f32_16x16x32_bf16 v[4:7], v[164:167], v[204:207], v[4:7]
	v_mfma_f32_16x16x32_bf16 v[0:3], v[172:175], v[204:207], v[0:3]
	v_mfma_f32_16x16x32_bf16 v[40:43], v[168:171], v[184:187], v[40:43]
	v_mfma_f32_16x16x32_bf16 v[32:35], v[176:179], v[184:187], v[32:35]
	v_mfma_f32_16x16x32_bf16 v[24:27], v[168:171], v[192:195], v[24:27]
	v_mfma_f32_16x16x32_bf16 v[20:23], v[176:179], v[192:195], v[20:23]
	v_mfma_f32_16x16x32_bf16 v[12:15], v[168:171], v[200:203], v[12:15]
	v_mfma_f32_16x16x32_bf16 v[8:11], v[176:179], v[200:203], v[8:11]
	v_mfma_f32_16x16x32_bf16 v[4:7], v[168:171], v[208:211], v[4:7]
	v_mfma_f32_16x16x32_bf16 v[0:3], v[176:179], v[208:211], v[0:3]
	s_setprio 1
	s_barrier
	s_add_i32 s59, s59, 2
	s_add_u32 s30, s30, 0x100
	s_addc_u32 s31, s31, 0
	s_add_u32 s56, s56, 0x100
	s_addc_u32 s57, s57, 0
	s_cmp_gt_u32 s59, 61
	s_cbranch_scc0 .LBB0_839
	s_and_b64 vcc, exec, s[8:9]
	s_cbranch_vccz .LBB0_842
	s_barrier
